# k32 + hot loop heads (14 GEMM K-loops, attention main and tail loops) aligned to 64 bytes
# speedup vs baseline: 1.0024x; 1.0009x over previous
.LBB0_444:
	s_add_u32 s48, s46, 0x20080
	s_addc_u32 s49, s47, 0
	s_add_u32 s25, s50, 0x100
	s_addc_u32 s64, s51, 0
	s_mov_b32 s65, -2
	s_add_u32 s46, s48, 0xfffe0080
	s_addc_u32 s47, s49, -1
	s_add_i32 s84, 0, 0x10000
	s_cmp_eq_u32 s65, 4
	s_cselect_b32 s47, s15, s47
	s_cselect_b32 s46, s14, s46
	v_add_u32_e32 v0, s84, v147
	s_cselect_b32 s51, s17, s64
	s_cselect_b32 s50, s16, s25
	s_add_i32 s86, 0, 0x14000
	ds_read_b128 v[150:153], v0
	ds_read_b128 v[154:157], v0 offset:1024
	ds_read_b128 v[158:161], v0 offset:2048
	ds_read_b128 v[162:165], v0 offset:3072
	ds_read_b128 v[166:169], v0 offset:16384
	ds_read_b128 v[170:173], v0 offset:17408
	ds_read_b128 v[174:177], v0 offset:18432
	ds_read_b128 v[178:181], v0 offset:19456
	ds_read_b128 v[182:185], v148
	ds_read_b128 v[186:189], v148 offset:1024
	ds_read_b128 v[190:193], v148 offset:2048
	ds_read_b128 v[194:197], v148 offset:3072
	ds_read_b128 v[198:201], v148 offset:4096
	ds_read_b128 v[202:205], v148 offset:5120
	ds_read_b128 v[206:209], v148 offset:6144
	ds_read_b128 v[210:213], v148 offset:7168
	s_add_i32 m0, s59, 0xc000
	s_nop 0
	global_load_lds_dwordx4 v132, s[48:49]
	s_add_i32 m0, s59, 0xe000
	s_nop 0
	global_load_lds_dwordx4 v133, s[48:49]
	s_waitcnt vmcnt(8)
	s_waitcnt lgkmcnt(0)
	s_barrier
	s_setprio 1
	s_waitcnt lgkmcnt(0)
	v_mfma_i32_16x16x64_i8 v[126:129], v[150:153], v[182:185], 0
	v_mfma_i32_16x16x64_i8 v[122:125], v[158:161], v[182:185], 0
	v_mfma_i32_16x16x64_i8 v[110:113], v[150:153], v[190:193], 0
	v_mfma_i32_16x16x64_i8 v[106:109], v[158:161], v[190:193], 0
	v_mfma_i32_16x16x64_i8 v[94:97], v[150:153], v[198:201], 0
	v_mfma_i32_16x16x64_i8 v[90:93], v[158:161], v[198:201], 0
	v_mfma_i32_16x16x64_i8 v[78:81], v[150:153], v[206:209], 0
	v_mfma_i32_16x16x64_i8 v[74:77], v[158:161], v[206:209], 0
	v_mfma_i32_16x16x64_i8 v[126:129], v[154:157], v[186:189], v[126:129]
	v_mfma_i32_16x16x64_i8 v[122:125], v[162:165], v[186:189], v[122:125]
	v_mfma_i32_16x16x64_i8 v[110:113], v[154:157], v[194:197], v[110:113]
	v_mfma_i32_16x16x64_i8 v[106:109], v[162:165], v[194:197], v[106:109]
	v_mfma_i32_16x16x64_i8 v[94:97], v[154:157], v[202:205], v[94:97]
	v_mfma_i32_16x16x64_i8 v[90:93], v[162:165], v[202:205], v[90:93]
	v_mfma_i32_16x16x64_i8 v[78:81], v[154:157], v[210:213], v[78:81]
	v_mfma_i32_16x16x64_i8 v[74:77], v[162:165], v[210:213], v[74:77]
	s_setprio 0
	s_setprio 1
	v_mfma_i32_16x16x64_i8 v[118:121], v[166:169], v[182:185], 0
	v_mfma_i32_16x16x64_i8 v[114:117], v[174:177], v[182:185], 0
	v_mfma_i32_16x16x64_i8 v[102:105], v[166:169], v[190:193], 0
	v_mfma_i32_16x16x64_i8 v[98:101], v[174:177], v[190:193], 0
	v_mfma_i32_16x16x64_i8 v[86:89], v[166:169], v[198:201], 0
	v_mfma_i32_16x16x64_i8 v[82:85], v[174:177], v[198:201], 0
	v_mfma_i32_16x16x64_i8 v[70:73], v[166:169], v[206:209], 0
	v_mfma_i32_16x16x64_i8 v[66:69], v[174:177], v[206:209], 0
	v_mfma_i32_16x16x64_i8 v[118:121], v[170:173], v[186:189], v[118:121]
	v_mfma_i32_16x16x64_i8 v[114:117], v[178:181], v[186:189], v[114:117]
	v_mfma_i32_16x16x64_i8 v[102:105], v[170:173], v[194:197], v[102:105]
	v_mfma_i32_16x16x64_i8 v[98:101], v[178:181], v[194:197], v[98:101]
	v_mfma_i32_16x16x64_i8 v[86:89], v[170:173], v[202:205], v[86:89]
	v_mfma_i32_16x16x64_i8 v[82:85], v[178:181], v[202:205], v[82:85]
	v_mfma_i32_16x16x64_i8 v[70:73], v[170:173], v[210:213], v[70:73]
	v_mfma_i32_16x16x64_i8 v[66:69], v[178:181], v[210:213], v[66:69]
	s_setprio 0
	s_barrier
	s_add_i32 s84, s84, s40
	ds_read_b128 v[182:185], v148 offset:16384
	ds_read_b128 v[186:189], v148 offset:17408
	ds_read_b128 v[190:193], v148 offset:18432
	ds_read_b128 v[194:197], v148 offset:19456
	ds_read_b128 v[198:201], v148 offset:20480
	ds_read_b128 v[202:205], v148 offset:21504
	ds_read_b128 v[206:209], v148 offset:22528
	ds_read_b128 v[210:213], v148 offset:23552
	s_mov_b32 m0, s84
	s_nop 0
	global_load_lds_dwordx4 v143, s[50:51]
	s_add_i32 m0, s84, 0x2000
	s_add_u32 s84, s50, 0x20000
	global_load_lds_dwordx4 v144, s[50:51]
	s_addc_u32 s85, s51, 0
	s_add_i32 s86, s86, s40
	s_mov_b32 m0, s86
	s_nop 0
	global_load_lds_dwordx4 v143, s[84:85]
	s_add_i32 m0, s86, 0x2000
	s_nop 0
	global_load_lds_dwordx4 v144, s[84:85]
	s_mov_b32 m0, s59
	s_nop 0
	global_load_lds_dwordx4 v132, s[46:47]
	s_mov_b32 m0, s60
	s_nop 0
	global_load_lds_dwordx4 v133, s[46:47]
	s_waitcnt vmcnt(8)
	s_waitcnt lgkmcnt(0)
	s_barrier
	s_setprio 1
	s_waitcnt lgkmcnt(0)
	v_mfma_i32_16x16x64_i8 v[62:65], v[150:153], v[182:185], 0
	v_mfma_i32_16x16x64_i8 v[58:61], v[158:161], v[182:185], 0
	v_mfma_i32_16x16x64_i8 v[46:49], v[150:153], v[190:193], 0
	v_mfma_i32_16x16x64_i8 v[42:45], v[158:161], v[190:193], 0
	v_mfma_i32_16x16x64_i8 v[30:33], v[150:153], v[198:201], 0
	v_mfma_i32_16x16x64_i8 v[26:29], v[158:161], v[198:201], 0
	v_mfma_i32_16x16x64_i8 v[14:17], v[150:153], v[206:209], 0
	v_mfma_i32_16x16x64_i8 v[10:13], v[158:161], v[206:209], 0
	v_mfma_i32_16x16x64_i8 v[62:65], v[154:157], v[186:189], v[62:65]
	v_mfma_i32_16x16x64_i8 v[58:61], v[162:165], v[186:189], v[58:61]
	v_mfma_i32_16x16x64_i8 v[46:49], v[154:157], v[194:197], v[46:49]
	v_mfma_i32_16x16x64_i8 v[42:45], v[162:165], v[194:197], v[42:45]
	v_mfma_i32_16x16x64_i8 v[30:33], v[154:157], v[202:205], v[30:33]
	v_mfma_i32_16x16x64_i8 v[26:29], v[162:165], v[202:205], v[26:29]
	v_mfma_i32_16x16x64_i8 v[14:17], v[154:157], v[210:213], v[14:17]
	v_mfma_i32_16x16x64_i8 v[10:13], v[162:165], v[210:213], v[10:13]
	s_setprio 0
	s_setprio 1
	v_mfma_i32_16x16x64_i8 v[54:57], v[166:169], v[182:185], 0
	v_mfma_i32_16x16x64_i8 v[50:53], v[174:177], v[182:185], 0
	v_mfma_i32_16x16x64_i8 v[38:41], v[166:169], v[190:193], 0
	v_mfma_i32_16x16x64_i8 v[34:37], v[174:177], v[190:193], 0
	v_mfma_i32_16x16x64_i8 v[22:25], v[166:169], v[198:201], 0
	v_mfma_i32_16x16x64_i8 v[18:21], v[174:177], v[198:201], 0
	v_mfma_i32_16x16x64_i8 v[6:9], v[166:169], v[206:209], 0
	v_mfma_i32_16x16x64_i8 v[2:5], v[174:177], v[206:209], 0
	v_mfma_i32_16x16x64_i8 v[54:57], v[170:173], v[186:189], v[54:57]
	v_mfma_i32_16x16x64_i8 v[50:53], v[178:181], v[186:189], v[50:53]
	v_mfma_i32_16x16x64_i8 v[38:41], v[170:173], v[194:197], v[38:41]
	v_mfma_i32_16x16x64_i8 v[34:37], v[178:181], v[194:197], v[34:37]
	v_mfma_i32_16x16x64_i8 v[22:25], v[170:173], v[202:205], v[22:25]
	v_mfma_i32_16x16x64_i8 v[18:21], v[178:181], v[202:205], v[18:21]
	v_mfma_i32_16x16x64_i8 v[6:9], v[170:173], v[210:213], v[6:9]
	v_mfma_i32_16x16x64_i8 v[2:5], v[178:181], v[210:213], v[2:5]
	s_setprio 0
	s_barrier
	s_add_i32 s86, 0, 0x18000
	s_add_i32 s87, 0, 0x1c000
	ds_read_b128 v[150:153], v0 offset:32768
	ds_read_b128 v[154:157], v0 offset:33792
	ds_read_b128 v[158:161], v0 offset:34816
	ds_read_b128 v[162:165], v0 offset:35840
	ds_read_b128 v[166:169], v0 offset:49152
	ds_read_b128 v[170:173], v0 offset:50176
	ds_read_b128 v[174:177], v0 offset:51200
	ds_read_b128 v[178:181], v0 offset:52224
	s_add_u32 s84, s46, 0x20000
	s_mov_b32 m0, s61
	ds_read_b128 v[182:185], v148 offset:32768
	ds_read_b128 v[186:189], v148 offset:33792
	ds_read_b128 v[190:193], v148 offset:34816
	ds_read_b128 v[194:197], v148 offset:35840
	ds_read_b128 v[198:201], v148 offset:36864
	ds_read_b128 v[202:205], v148 offset:37888
	ds_read_b128 v[206:209], v148 offset:38912
	ds_read_b128 v[210:213], v148 offset:39936
	s_addc_u32 s85, s47, 0
	s_nop 0
	global_load_lds_dwordx4 v132, s[84:85]
	s_mov_b32 m0, s66
	s_nop 0
	global_load_lds_dwordx4 v133, s[84:85]
	s_waitcnt vmcnt(8)
	s_waitcnt lgkmcnt(0)
	s_barrier
	s_setprio 1
	s_waitcnt lgkmcnt(0)
	v_mfma_i32_16x16x64_i8 v[126:129], v[150:153], v[182:185], v[126:129]
	v_mfma_i32_16x16x64_i8 v[122:125], v[158:161], v[182:185], v[122:125]
	v_mfma_i32_16x16x64_i8 v[110:113], v[150:153], v[190:193], v[110:113]
	v_mfma_i32_16x16x64_i8 v[106:109], v[158:161], v[190:193], v[106:109]
	v_mfma_i32_16x16x64_i8 v[94:97], v[150:153], v[198:201], v[94:97]
	v_mfma_i32_16x16x64_i8 v[90:93], v[158:161], v[198:201], v[90:93]
	v_mfma_i32_16x16x64_i8 v[78:81], v[150:153], v[206:209], v[78:81]
	v_mfma_i32_16x16x64_i8 v[74:77], v[158:161], v[206:209], v[74:77]
	v_mfma_i32_16x16x64_i8 v[126:129], v[154:157], v[186:189], v[126:129]
	v_mfma_i32_16x16x64_i8 v[122:125], v[162:165], v[186:189], v[122:125]
	v_mfma_i32_16x16x64_i8 v[110:113], v[154:157], v[194:197], v[110:113]
	v_mfma_i32_16x16x64_i8 v[106:109], v[162:165], v[194:197], v[106:109]
	v_mfma_i32_16x16x64_i8 v[94:97], v[154:157], v[202:205], v[94:97]
	v_mfma_i32_16x16x64_i8 v[90:93], v[162:165], v[202:205], v[90:93]
	v_mfma_i32_16x16x64_i8 v[78:81], v[154:157], v[210:213], v[78:81]
	v_mfma_i32_16x16x64_i8 v[74:77], v[162:165], v[210:213], v[74:77]
	s_setprio 0
	s_setprio 1
	v_mfma_i32_16x16x64_i8 v[118:121], v[166:169], v[182:185], v[118:121]
	v_mfma_i32_16x16x64_i8 v[114:117], v[174:177], v[182:185], v[114:117]
	v_mfma_i32_16x16x64_i8 v[102:105], v[166:169], v[190:193], v[102:105]
	v_mfma_i32_16x16x64_i8 v[98:101], v[174:177], v[190:193], v[98:101]
	v_mfma_i32_16x16x64_i8 v[86:89], v[166:169], v[198:201], v[86:89]
	v_mfma_i32_16x16x64_i8 v[82:85], v[174:177], v[198:201], v[82:85]
	v_mfma_i32_16x16x64_i8 v[70:73], v[166:169], v[206:209], v[70:73]
	v_mfma_i32_16x16x64_i8 v[66:69], v[174:177], v[206:209], v[66:69]
	v_mfma_i32_16x16x64_i8 v[118:121], v[170:173], v[186:189], v[118:121]
	v_mfma_i32_16x16x64_i8 v[114:117], v[178:181], v[186:189], v[114:117]
	v_mfma_i32_16x16x64_i8 v[102:105], v[170:173], v[194:197], v[102:105]
	v_mfma_i32_16x16x64_i8 v[98:101], v[178:181], v[194:197], v[98:101]
	v_mfma_i32_16x16x64_i8 v[86:89], v[170:173], v[202:205], v[86:89]
	v_mfma_i32_16x16x64_i8 v[82:85], v[178:181], v[202:205], v[82:85]
	v_mfma_i32_16x16x64_i8 v[70:73], v[170:173], v[210:213], v[70:73]
	v_mfma_i32_16x16x64_i8 v[66:69], v[178:181], v[210:213], v[66:69]
	s_setprio 0
	s_barrier
	ds_read_b128 v[182:185], v148 offset:49152
	ds_read_b128 v[186:189], v148 offset:50176
	ds_read_b128 v[190:193], v148 offset:51200
	ds_read_b128 v[194:197], v148 offset:52224
	ds_read_b128 v[198:201], v148 offset:53248
	ds_read_b128 v[202:205], v148 offset:54272
	ds_read_b128 v[206:209], v148 offset:55296
	ds_read_b128 v[210:213], v148 offset:56320
	s_add_i32 s84, s86, s40
	s_add_u32 s100, s50, s38
	s_addc_u32 s101, s51, s39
	s_mov_b32 m0, s84
	s_nop 0
	global_load_lds_dwordx4 v143, s[100:101]
	s_add_i32 m0, s84, 0x2000
	s_nop 0
	s_add_u32 s50, s50, 0x20080
	s_addc_u32 s51, s51, 0
	s_add_i32 s84, s87, s40
	global_load_lds_dwordx4 v144, s[100:101]
	s_mov_b32 m0, s84
	s_nop 0
	global_load_lds_dwordx4 v143, s[50:51]
	s_add_i32 m0, s84, 0x2000
	s_nop 0
	global_load_lds_dwordx4 v144, s[50:51]
	s_mov_b32 m0, s75
	s_add_u32 s100, s46, s38
	s_addc_u32 s101, s47, s39
	v_mov_b32_e32 v0, v133
	global_load_lds_dwordx4 v132, s[100:101]
	s_mov_b32 m0, s78
	s_nop 0
	global_load_lds_dwordx4 v133, s[100:101]
	s_waitcnt vmcnt(8)
	s_waitcnt lgkmcnt(0)
	s_barrier
	s_setprio 1
	s_waitcnt lgkmcnt(0)
	v_mfma_i32_16x16x64_i8 v[62:65], v[150:153], v[182:185], v[62:65]
	v_mfma_i32_16x16x64_i8 v[58:61], v[158:161], v[182:185], v[58:61]
	v_mfma_i32_16x16x64_i8 v[46:49], v[150:153], v[190:193], v[46:49]
	v_mfma_i32_16x16x64_i8 v[42:45], v[158:161], v[190:193], v[42:45]
	v_mfma_i32_16x16x64_i8 v[30:33], v[150:153], v[198:201], v[30:33]
	v_mfma_i32_16x16x64_i8 v[26:29], v[158:161], v[198:201], v[26:29]
	v_mfma_i32_16x16x64_i8 v[14:17], v[150:153], v[206:209], v[14:17]
	v_mfma_i32_16x16x64_i8 v[10:13], v[158:161], v[206:209], v[10:13]
	v_mfma_i32_16x16x64_i8 v[62:65], v[154:157], v[186:189], v[62:65]
	v_mfma_i32_16x16x64_i8 v[58:61], v[162:165], v[186:189], v[58:61]
	v_mfma_i32_16x16x64_i8 v[46:49], v[154:157], v[194:197], v[46:49]
	v_mfma_i32_16x16x64_i8 v[42:45], v[162:165], v[194:197], v[42:45]
	v_mfma_i32_16x16x64_i8 v[30:33], v[154:157], v[202:205], v[30:33]
	v_mfma_i32_16x16x64_i8 v[26:29], v[162:165], v[202:205], v[26:29]
	v_mfma_i32_16x16x64_i8 v[14:17], v[154:157], v[210:213], v[14:17]
	v_mfma_i32_16x16x64_i8 v[10:13], v[162:165], v[210:213], v[10:13]
	s_setprio 0
	s_setprio 1
	v_mfma_i32_16x16x64_i8 v[54:57], v[166:169], v[182:185], v[54:57]
	v_mfma_i32_16x16x64_i8 v[50:53], v[174:177], v[182:185], v[50:53]
	v_mfma_i32_16x16x64_i8 v[38:41], v[166:169], v[190:193], v[38:41]
	v_mfma_i32_16x16x64_i8 v[34:37], v[174:177], v[190:193], v[34:37]
	v_mfma_i32_16x16x64_i8 v[22:25], v[166:169], v[198:201], v[22:25]
	v_mfma_i32_16x16x64_i8 v[18:21], v[174:177], v[198:201], v[18:21]
	v_mfma_i32_16x16x64_i8 v[6:9], v[166:169], v[206:209], v[6:9]
	v_mfma_i32_16x16x64_i8 v[2:5], v[174:177], v[206:209], v[2:5]
	v_mfma_i32_16x16x64_i8 v[54:57], v[170:173], v[186:189], v[54:57]
	v_mfma_i32_16x16x64_i8 v[50:53], v[178:181], v[186:189], v[50:53]
	v_mfma_i32_16x16x64_i8 v[38:41], v[170:173], v[194:197], v[38:41]
	v_mfma_i32_16x16x64_i8 v[34:37], v[178:181], v[194:197], v[34:37]
	v_mfma_i32_16x16x64_i8 v[22:25], v[170:173], v[202:205], v[22:25]
	v_mfma_i32_16x16x64_i8 v[18:21], v[178:181], v[202:205], v[18:21]
	v_mfma_i32_16x16x64_i8 v[6:9], v[170:173], v[210:213], v[6:9]
	v_mfma_i32_16x16x64_i8 v[2:5], v[178:181], v[210:213], v[2:5]
	s_setprio 0
	s_barrier
	s_add_i32 s65, s65, 2
	s_add_u32 s48, s48, 0x100
	s_addc_u32 s49, s49, 0
	s_add_u32 s25, s25, 0x100
	s_addc_u32 s64, s64, 0
	s_cmp_gt_u32 s65, 5
	s_cbranch_scc0 .LBB0_445
	s_branch .Lpeel_exit_445
	.p2align	6

.LBB0_625:
	v_bfe_u32 v134, v0, 4, 2
	v_and_b32_e32 v135, 15, v0
	v_lshlrev_b32_e32 v2, 4, v134
	v_lshlrev_b32_e32 v0, 2, v0
	s_lshl_b32 s61, s4, 6
	v_lshl_or_b32 v2, v135, 6, v2
	s_lshl_b32 s4, s4, 13
	v_and_b32_e32 v0, 32, v0
	v_bitop3_b32 v4, v2, s4, v0 bitop3:0xde
	s_lshl_b32 s4, s5, 5
	s_and_b32 s64, s4, 0x60
	s_lshl_b32 s4, s64, 7
	v_bitop3_b32 v136, s4, v2, v0 bitop3:0xf6
	v_mov_b32_e32 v0, v131
	s_waitcnt vmcnt(2)
	s_barrier
	s_add_i32 m0, s43, 0x18000
	v_lshl_add_u64 v[2:3], s[16:17], 0, v[0:1]
	v_lshl_add_u64 v[2:3], v[2:3], 0, s[38:39]
	v_mov_b32_e32 v0, v133
	global_load_lds_dwordx4 v[2:3], off
	s_add_i32 m0, s43, 0x1a000
	v_lshl_add_u64 v[2:3], s[16:17], 0, v[0:1]
	v_lshl_add_u64 v[2:3], v[2:3], 0, s[38:39]
	v_mov_b32_e32 v0, v130
	global_load_lds_dwordx4 v[2:3], off
	s_add_i32 s67, s43, 0x8000
	v_lshl_add_u64 v[2:3], s[14:15], 0, v[0:1]
	v_lshl_add_u64 v[2:3], v[2:3], 0, s[38:39]
	s_mov_b32 m0, s67
	v_mov_b32_e32 v0, v132
	global_load_lds_dwordx4 v[2:3], off
	s_add_i32 s68, s43, 0xa000
	v_lshl_add_u64 v[2:3], s[14:15], 0, v[0:1]
	v_lshl_add_u64 v[2:3], v[2:3], 0, s[38:39]
	s_mov_b32 m0, s68
	s_add_u32 s4, s16, 0x40080
	v_mov_b32_e32 v0, v131
	global_load_lds_dwordx4 v[2:3], off
	s_addc_u32 s5, s17, 0
	s_add_i32 m0, s43, 0x1c000
	v_mov_b32_e32 v2, 0
	global_load_lds_dwordx4 v0, s[4:5]
	v_mov_b32_e32 v0, v133
	s_add_i32 m0, s43, 0x1e000
	s_mov_b64 s[50:51], 0
	global_load_lds_dwordx4 v0, s[4:5]
	s_waitcnt vmcnt(6)
	s_mov_b64 s[22:23], -1
	s_mov_b64 s[48:49], 0
	v_add_u32_e32 v137, 0, v4
	v_mov_b32_e32 v3, v2
	v_mov_b32_e32 v4, v2
	v_mov_b32_e32 v5, v2
	v_mov_b32_e32 v6, v2
	v_mov_b32_e32 v7, v2
	v_mov_b32_e32 v8, v2
	v_mov_b32_e32 v9, v2
	v_mov_b32_e32 v10, v2
	v_mov_b32_e32 v11, v2
	v_mov_b32_e32 v12, v2
	v_mov_b32_e32 v13, v2
	v_mov_b32_e32 v18, v2
	v_mov_b32_e32 v19, v2
	v_mov_b32_e32 v20, v2
	v_mov_b32_e32 v21, v2
	v_mov_b32_e32 v26, v2
	v_mov_b32_e32 v27, v2
	v_mov_b32_e32 v28, v2
	v_mov_b32_e32 v29, v2
	v_mov_b32_e32 v34, v2
	v_mov_b32_e32 v35, v2
	v_mov_b32_e32 v36, v2
	v_mov_b32_e32 v37, v2
	v_mov_b32_e32 v42, v2
	v_mov_b32_e32 v43, v2
	v_mov_b32_e32 v44, v2
	v_mov_b32_e32 v45, v2
	v_mov_b32_e32 v50, v2
	v_mov_b32_e32 v51, v2
	v_mov_b32_e32 v52, v2
	v_mov_b32_e32 v53, v2
	v_mov_b32_e32 v14, v2
	v_mov_b32_e32 v15, v2
	v_mov_b32_e32 v16, v2
	v_mov_b32_e32 v17, v2
	v_mov_b32_e32 v22, v2
	v_mov_b32_e32 v23, v2
	v_mov_b32_e32 v24, v2
	v_mov_b32_e32 v25, v2
	v_mov_b32_e32 v30, v2
	v_mov_b32_e32 v31, v2
	v_mov_b32_e32 v32, v2
	v_mov_b32_e32 v33, v2
	v_mov_b32_e32 v38, v2
	v_mov_b32_e32 v39, v2
	v_mov_b32_e32 v40, v2
	v_mov_b32_e32 v41, v2
	v_mov_b32_e32 v46, v2
	v_mov_b32_e32 v47, v2
	v_mov_b32_e32 v48, v2
	v_mov_b32_e32 v49, v2
	v_mov_b32_e32 v54, v2
	v_mov_b32_e32 v55, v2
	v_mov_b32_e32 v56, v2
	v_mov_b32_e32 v57, v2
	v_mov_b32_e32 v58, v2
	v_mov_b32_e32 v59, v2
	v_mov_b32_e32 v60, v2
	v_mov_b32_e32 v61, v2
	v_mov_b32_e32 v66, v2
	v_mov_b32_e32 v67, v2
	v_mov_b32_e32 v68, v2
	v_mov_b32_e32 v69, v2
	v_mov_b32_e32 v62, v2
	v_mov_b32_e32 v63, v2
	v_mov_b32_e32 v64, v2
	v_mov_b32_e32 v65, v2
	v_mov_b32_e32 v70, v2
	v_mov_b32_e32 v71, v2
	v_mov_b32_e32 v72, v2
	v_mov_b32_e32 v73, v2
	v_mov_b32_e32 v74, v2
	v_mov_b32_e32 v75, v2
	v_mov_b32_e32 v76, v2
	v_mov_b32_e32 v77, v2
	v_mov_b32_e32 v82, v2
	v_mov_b32_e32 v83, v2
	v_mov_b32_e32 v84, v2
	v_mov_b32_e32 v85, v2
	v_mov_b32_e32 v90, v2
	v_mov_b32_e32 v91, v2
	v_mov_b32_e32 v92, v2
	v_mov_b32_e32 v93, v2
	v_mov_b32_e32 v98, v2
	v_mov_b32_e32 v99, v2
	v_mov_b32_e32 v100, v2
	v_mov_b32_e32 v101, v2
	v_mov_b32_e32 v106, v2
	v_mov_b32_e32 v107, v2
	v_mov_b32_e32 v108, v2
	v_mov_b32_e32 v109, v2
	v_mov_b32_e32 v114, v2
	v_mov_b32_e32 v115, v2
	v_mov_b32_e32 v116, v2
	v_mov_b32_e32 v117, v2
	v_mov_b32_e32 v78, v2
	v_mov_b32_e32 v79, v2
	v_mov_b32_e32 v80, v2
	v_mov_b32_e32 v81, v2
	v_mov_b32_e32 v86, v2
	v_mov_b32_e32 v87, v2
	v_mov_b32_e32 v88, v2
	v_mov_b32_e32 v89, v2
	v_mov_b32_e32 v94, v2
	v_mov_b32_e32 v95, v2
	v_mov_b32_e32 v96, v2
	v_mov_b32_e32 v97, v2
	v_mov_b32_e32 v102, v2
	v_mov_b32_e32 v103, v2
	v_mov_b32_e32 v104, v2
	v_mov_b32_e32 v105, v2
	v_mov_b32_e32 v110, v2
	v_mov_b32_e32 v111, v2
	v_mov_b32_e32 v112, v2
	v_mov_b32_e32 v113, v2
	v_mov_b32_e32 v118, v2
	v_mov_b32_e32 v119, v2
	v_mov_b32_e32 v120, v2
	v_mov_b32_e32 v121, v2
	v_mov_b32_e32 v122, v2
	v_mov_b32_e32 v123, v2
	v_mov_b32_e32 v124, v2
	v_mov_b32_e32 v125, v2
	v_mov_b32_e32 v126, v2
	v_mov_b32_e32 v127, v2
	v_mov_b32_e32 v128, v2
	v_mov_b32_e32 v129, v2
	s_barrier
	.p2align	6

.LBB0_633:
	v_bfe_u32 v134, v2, 4, 2
	s_add_u32 s65, s14, 0x800
	v_and_b32_e32 v135, 15, v2
	v_lshlrev_b32_e32 v0, 4, v134
	v_lshlrev_b32_e32 v2, 2, v2
	s_addc_u32 s66, s15, 0
	s_lshl_b32 s60, s4, 6
	v_lshl_or_b32 v0, v135, 6, v0
	s_lshl_b32 s4, s4, 13
	v_and_b32_e32 v2, 32, v2
	v_bitop3_b32 v4, v0, s4, v2 bitop3:0xde
	s_lshl_b32 s4, s5, 5
	s_and_b32 s61, s4, 0x60
	s_lshl_b32 s4, s61, 7
	v_bitop3_b32 v136, s4, v0, v2 bitop3:0xf6
	v_mov_b32_e32 v0, v131
	s_waitcnt vmcnt(2)
	s_barrier
	s_mov_b64 s[4:5], 0x880
	v_lshl_add_u64 v[2:3], s[14:15], 0, v[0:1]
	s_add_i32 m0, s41, 0x18000
	v_lshl_add_u64 v[2:3], v[2:3], 0, s[4:5]
	v_mov_b32_e32 v0, v133
	global_load_lds_dwordx4 v[2:3], off
	s_add_i32 m0, s41, 0x1a000
	v_lshl_add_u64 v[2:3], s[14:15], 0, v[0:1]
	v_lshl_add_u64 v[2:3], v[2:3], 0, s[4:5]
	v_mov_b32_e32 v0, v130
	global_load_lds_dwordx4 v[2:3], off
	s_add_i32 s67, s41, 0x8000
	v_lshl_add_u64 v[2:3], s[2:3], 0, v[0:1]
	v_lshl_add_u64 v[2:3], v[2:3], 0, s[38:39]
	s_mov_b32 m0, s67
	v_mov_b32_e32 v0, v132
	global_load_lds_dwordx4 v[2:3], off
	s_add_i32 s68, s41, 0xa000
	v_lshl_add_u64 v[2:3], s[2:3], 0, v[0:1]
	v_lshl_add_u64 v[2:3], v[2:3], 0, s[38:39]
	s_mov_b32 m0, s68
	s_add_u32 s4, s14, 0x80880
	v_mov_b32_e32 v0, v131
	global_load_lds_dwordx4 v[2:3], off
	s_addc_u32 s5, s15, 0
	s_add_i32 m0, s41, 0x1c000
	v_mov_b32_e32 v2, 0
	global_load_lds_dwordx4 v0, s[4:5]
	v_mov_b32_e32 v0, v133
	s_add_i32 m0, s41, 0x1e000
	s_mov_b64 s[48:49], 0
	global_load_lds_dwordx4 v0, s[4:5]
	s_waitcnt vmcnt(6)
	s_mov_b64 s[16:17], -1
	s_mov_b64 s[46:47], 0
	v_add_u32_e32 v137, 0, v4
	v_mov_b32_e32 v3, v2
	v_mov_b32_e32 v4, v2
	v_mov_b32_e32 v5, v2
	v_mov_b32_e32 v6, v2
	v_mov_b32_e32 v7, v2
	v_mov_b32_e32 v8, v2
	v_mov_b32_e32 v9, v2
	v_mov_b32_e32 v10, v2
	v_mov_b32_e32 v11, v2
	v_mov_b32_e32 v12, v2
	v_mov_b32_e32 v13, v2
	v_mov_b32_e32 v18, v2
	v_mov_b32_e32 v19, v2
	v_mov_b32_e32 v20, v2
	v_mov_b32_e32 v21, v2
	v_mov_b32_e32 v26, v2
	v_mov_b32_e32 v27, v2
	v_mov_b32_e32 v28, v2
	v_mov_b32_e32 v29, v2
	v_mov_b32_e32 v34, v2
	v_mov_b32_e32 v35, v2
	v_mov_b32_e32 v36, v2
	v_mov_b32_e32 v37, v2
	v_mov_b32_e32 v42, v2
	v_mov_b32_e32 v43, v2
	v_mov_b32_e32 v44, v2
	v_mov_b32_e32 v45, v2
	v_mov_b32_e32 v50, v2
	v_mov_b32_e32 v51, v2
	v_mov_b32_e32 v52, v2
	v_mov_b32_e32 v53, v2
	v_mov_b32_e32 v14, v2
	v_mov_b32_e32 v15, v2
	v_mov_b32_e32 v16, v2
	v_mov_b32_e32 v17, v2
	v_mov_b32_e32 v22, v2
	v_mov_b32_e32 v23, v2
	v_mov_b32_e32 v24, v2
	v_mov_b32_e32 v25, v2
	v_mov_b32_e32 v30, v2
	v_mov_b32_e32 v31, v2
	v_mov_b32_e32 v32, v2
	v_mov_b32_e32 v33, v2
	v_mov_b32_e32 v38, v2
	v_mov_b32_e32 v39, v2
	v_mov_b32_e32 v40, v2
	v_mov_b32_e32 v41, v2
	v_mov_b32_e32 v46, v2
	v_mov_b32_e32 v47, v2
	v_mov_b32_e32 v48, v2
	v_mov_b32_e32 v49, v2
	v_mov_b32_e32 v54, v2
	v_mov_b32_e32 v55, v2
	v_mov_b32_e32 v56, v2
	v_mov_b32_e32 v57, v2
	v_mov_b32_e32 v58, v2
	v_mov_b32_e32 v59, v2
	v_mov_b32_e32 v60, v2
	v_mov_b32_e32 v61, v2
	v_mov_b32_e32 v66, v2
	v_mov_b32_e32 v67, v2
	v_mov_b32_e32 v68, v2
	v_mov_b32_e32 v69, v2
	v_mov_b32_e32 v62, v2
	v_mov_b32_e32 v63, v2
	v_mov_b32_e32 v64, v2
	v_mov_b32_e32 v65, v2
	v_mov_b32_e32 v70, v2
	v_mov_b32_e32 v71, v2
	v_mov_b32_e32 v72, v2
	v_mov_b32_e32 v73, v2
	v_mov_b32_e32 v74, v2
	v_mov_b32_e32 v75, v2
	v_mov_b32_e32 v76, v2
	v_mov_b32_e32 v77, v2
	v_mov_b32_e32 v82, v2
	v_mov_b32_e32 v83, v2
	v_mov_b32_e32 v84, v2
	v_mov_b32_e32 v85, v2
	v_mov_b32_e32 v90, v2
	v_mov_b32_e32 v91, v2
	v_mov_b32_e32 v92, v2
	v_mov_b32_e32 v93, v2
	v_mov_b32_e32 v98, v2
	v_mov_b32_e32 v99, v2
	v_mov_b32_e32 v100, v2
	v_mov_b32_e32 v101, v2
	v_mov_b32_e32 v106, v2
	v_mov_b32_e32 v107, v2
	v_mov_b32_e32 v108, v2
	v_mov_b32_e32 v109, v2
	v_mov_b32_e32 v114, v2
	v_mov_b32_e32 v115, v2
	v_mov_b32_e32 v116, v2
	v_mov_b32_e32 v117, v2
	v_mov_b32_e32 v78, v2
	v_mov_b32_e32 v79, v2
	v_mov_b32_e32 v80, v2
	v_mov_b32_e32 v81, v2
	v_mov_b32_e32 v86, v2
	v_mov_b32_e32 v87, v2
	v_mov_b32_e32 v88, v2
	v_mov_b32_e32 v89, v2
	v_mov_b32_e32 v94, v2
	v_mov_b32_e32 v95, v2
	v_mov_b32_e32 v96, v2
	v_mov_b32_e32 v97, v2
	v_mov_b32_e32 v102, v2
	v_mov_b32_e32 v103, v2
	v_mov_b32_e32 v104, v2
	v_mov_b32_e32 v105, v2
	v_mov_b32_e32 v110, v2
	v_mov_b32_e32 v111, v2
	v_mov_b32_e32 v112, v2
	v_mov_b32_e32 v113, v2
	v_mov_b32_e32 v118, v2
	v_mov_b32_e32 v119, v2
	v_mov_b32_e32 v120, v2
	v_mov_b32_e32 v121, v2
	v_mov_b32_e32 v122, v2
	v_mov_b32_e32 v123, v2
	v_mov_b32_e32 v124, v2
	v_mov_b32_e32 v125, v2
	v_mov_b32_e32 v126, v2
	v_mov_b32_e32 v127, v2
	v_mov_b32_e32 v128, v2
	v_mov_b32_e32 v129, v2
	s_barrier
	.p2align	6

.LBB0_666:
	v_bfe_u32 v143, v0, 4, 2
	v_or_b32_e32 v0, s50, v140
	s_and_b32 s64, s5, 3
	v_lshlrev_b32_e32 v2, 4, v143
	v_lshlrev_b32_e32 v3, 6, v0
	s_movk_i32 s5, 0x3c0
	v_lshlrev_b32_e32 v0, 2, v0
	v_and_or_b32 v3, v3, s5, v2
	s_lshl_b32 s5, s47, 13
	v_and_b32_e32 v0, 32, v0
	v_bitop3_b32 v4, v3, s5, v0 bitop3:0xde
	v_lshl_or_b32 v0, v140, 6, v2
	v_lshlrev_b32_e32 v2, 2, v140
	s_lshl_b32 s5, s64, 12
	v_and_b32_e32 v2, 32, v2
	v_bitop3_b32 v144, v0, s5, v2 bitop3:0xde
	v_mov_b32_e32 v0, v131
	s_waitcnt vmcnt(2)
	s_barrier
	s_add_i32 m0, s61, 0x18000
	v_lshl_add_u64 v[2:3], s[48:49], 0, v[0:1]
	v_lshl_add_u64 v[2:3], v[2:3], 0, s[38:39]
	v_mov_b32_e32 v0, v142
	global_load_lds_dwordx4 v[2:3], off
	s_add_i32 m0, s61, 0x1a000
	v_lshl_add_u64 v[2:3], s[48:49], 0, v[0:1]
	v_lshl_add_u64 v[2:3], v[2:3], 0, s[38:39]
	v_mov_b32_e32 v0, v130
	global_load_lds_dwordx4 v[2:3], off
	s_add_i32 s68, s61, 0x8000
	v_lshl_add_u64 v[2:3], s[22:23], 0, v[0:1]
	v_lshl_add_u64 v[2:3], v[2:3], 0, s[38:39]
	s_mov_b32 m0, s68
	v_mov_b32_e32 v0, v141
	global_load_lds_dwordx4 v[2:3], off
	s_add_i32 s69, s61, 0xa000
	v_lshl_add_u64 v[2:3], s[22:23], 0, v[0:1]
	v_lshl_add_u64 v[2:3], v[2:3], 0, s[38:39]
	s_mov_b32 m0, s69
	s_add_u32 s50, s48, 0x20080
	v_mov_b32_e32 v0, v131
	global_load_lds_dwordx4 v[2:3], off
	s_addc_u32 s51, s49, 0
	s_add_i32 m0, s61, 0x1c000
	v_mov_b32_e32 v2, 0
	global_load_lds_dwordx4 v0, s[50:51]
	v_mov_b32_e32 v0, v142
	s_add_i32 m0, s61, 0x1e000
	s_add_u32 s70, s14, s25
	global_load_lds_dwordx4 v0, s[50:51]
	s_addc_u32 s71, s15, 0
	s_add_u32 s4, s46, s4
	s_addc_u32 s5, 0, 0
	s_add_u32 s4, s14, s4
	s_waitcnt vmcnt(6)
	s_addc_u32 s5, s15, s5
	s_add_u32 s74, s4, 0x1680100
	s_addc_u32 s75, s5, 0
	s_mov_b32 s76, -2
	s_mov_b64 s[50:51], 0
	v_add_u32_e32 v145, 0, v4
	v_mov_b32_e32 v3, v2
	v_mov_b32_e32 v4, v2
	v_mov_b32_e32 v5, v2
	v_mov_b32_e32 v6, v2
	v_mov_b32_e32 v7, v2
	v_mov_b32_e32 v8, v2
	v_mov_b32_e32 v9, v2
	v_mov_b32_e32 v18, v2
	v_mov_b32_e32 v19, v2
	v_mov_b32_e32 v20, v2
	v_mov_b32_e32 v21, v2
	v_mov_b32_e32 v22, v2
	v_mov_b32_e32 v23, v2
	v_mov_b32_e32 v24, v2
	v_mov_b32_e32 v25, v2
	v_mov_b32_e32 v34, v2
	v_mov_b32_e32 v35, v2
	v_mov_b32_e32 v36, v2
	v_mov_b32_e32 v37, v2
	v_mov_b32_e32 v38, v2
	v_mov_b32_e32 v39, v2
	v_mov_b32_e32 v40, v2
	v_mov_b32_e32 v41, v2
	v_mov_b32_e32 v50, v2
	v_mov_b32_e32 v51, v2
	v_mov_b32_e32 v52, v2
	v_mov_b32_e32 v53, v2
	v_mov_b32_e32 v54, v2
	v_mov_b32_e32 v55, v2
	v_mov_b32_e32 v56, v2
	v_mov_b32_e32 v57, v2
	v_mov_b32_e32 v10, v2
	v_mov_b32_e32 v11, v2
	v_mov_b32_e32 v12, v2
	v_mov_b32_e32 v13, v2
	v_mov_b32_e32 v14, v2
	v_mov_b32_e32 v15, v2
	v_mov_b32_e32 v16, v2
	v_mov_b32_e32 v17, v2
	v_mov_b32_e32 v26, v2
	v_mov_b32_e32 v27, v2
	v_mov_b32_e32 v28, v2
	v_mov_b32_e32 v29, v2
	v_mov_b32_e32 v30, v2
	v_mov_b32_e32 v31, v2
	v_mov_b32_e32 v32, v2
	v_mov_b32_e32 v33, v2
	v_mov_b32_e32 v42, v2
	v_mov_b32_e32 v43, v2
	v_mov_b32_e32 v44, v2
	v_mov_b32_e32 v45, v2
	v_mov_b32_e32 v46, v2
	v_mov_b32_e32 v47, v2
	v_mov_b32_e32 v48, v2
	v_mov_b32_e32 v49, v2
	v_mov_b32_e32 v58, v2
	v_mov_b32_e32 v59, v2
	v_mov_b32_e32 v60, v2
	v_mov_b32_e32 v61, v2
	v_mov_b32_e32 v62, v2
	v_mov_b32_e32 v63, v2
	v_mov_b32_e32 v64, v2
	v_mov_b32_e32 v65, v2
	v_mov_b32_e32 v66, v2
	v_mov_b32_e32 v67, v2
	v_mov_b32_e32 v68, v2
	v_mov_b32_e32 v69, v2
	v_mov_b32_e32 v70, v2
	v_mov_b32_e32 v71, v2
	v_mov_b32_e32 v72, v2
	v_mov_b32_e32 v73, v2
	v_mov_b32_e32 v82, v2
	v_mov_b32_e32 v83, v2
	v_mov_b32_e32 v84, v2
	v_mov_b32_e32 v85, v2
	v_mov_b32_e32 v86, v2
	v_mov_b32_e32 v87, v2
	v_mov_b32_e32 v88, v2
	v_mov_b32_e32 v89, v2
	v_mov_b32_e32 v98, v2
	v_mov_b32_e32 v99, v2
	v_mov_b32_e32 v100, v2
	v_mov_b32_e32 v101, v2
	v_mov_b32_e32 v102, v2
	v_mov_b32_e32 v103, v2
	v_mov_b32_e32 v104, v2
	v_mov_b32_e32 v105, v2
	v_mov_b32_e32 v114, v2
	v_mov_b32_e32 v115, v2
	v_mov_b32_e32 v116, v2
	v_mov_b32_e32 v117, v2
	v_mov_b32_e32 v118, v2
	v_mov_b32_e32 v119, v2
	v_mov_b32_e32 v120, v2
	v_mov_b32_e32 v121, v2
	v_mov_b32_e32 v74, v2
	v_mov_b32_e32 v75, v2
	v_mov_b32_e32 v76, v2
	v_mov_b32_e32 v77, v2
	v_mov_b32_e32 v78, v2
	v_mov_b32_e32 v79, v2
	v_mov_b32_e32 v80, v2
	v_mov_b32_e32 v81, v2
	v_mov_b32_e32 v90, v2
	v_mov_b32_e32 v91, v2
	v_mov_b32_e32 v92, v2
	v_mov_b32_e32 v93, v2
	v_mov_b32_e32 v94, v2
	v_mov_b32_e32 v95, v2
	v_mov_b32_e32 v96, v2
	v_mov_b32_e32 v97, v2
	v_mov_b32_e32 v106, v2
	v_mov_b32_e32 v107, v2
	v_mov_b32_e32 v108, v2
	v_mov_b32_e32 v109, v2
	v_mov_b32_e32 v110, v2
	v_mov_b32_e32 v111, v2
	v_mov_b32_e32 v112, v2
	v_mov_b32_e32 v113, v2
	v_mov_b32_e32 v122, v2
	v_mov_b32_e32 v123, v2
	v_mov_b32_e32 v124, v2
	v_mov_b32_e32 v125, v2
	v_mov_b32_e32 v126, v2
	v_mov_b32_e32 v127, v2
	v_mov_b32_e32 v128, v2
	v_mov_b32_e32 v129, v2
	s_barrier
	.p2align	6

.LBB0_820:
	s_lshr_b32 s61, s77, 6
	s_mul_i32 s46, s61, 0x160000
	s_add_u32 s70, s37, s46
	s_addc_u32 s71, s76, 0
	s_and_b32 s41, s4, 3
	v_lshlrev_b32_e32 v8, 1, v2
	v_lshrrev_b32_e32 v9, 2, v2
	v_and_b32_e32 v3, 3, v3
	s_mov_b32 s4, 0xffffe0
	v_and_b32_e32 v8, 24, v8
	v_and_b32_e32 v9, 4, v9
	v_and_or_b32 v2, v2, s4, v3
	v_or3_b32 v2, v2, v9, v8
	v_mul_u32_u24_e32 v2, 0xb00, v2
	v_add_lshl_u32 v132, v2, v4, 1
	v_lshlrev_b32_e32 v2, 1, v5
	v_lshrrev_b32_e32 v3, 2, v5
	v_and_b32_e32 v4, 3, v6
	v_and_b32_e32 v2, 24, v2
	v_and_b32_e32 v3, 4, v3
	v_and_or_b32 v4, v5, s4, v4
	v_or3_b32 v2, v4, v3, v2
	v_mul_u32_u24_e32 v2, 0xb00, v2
	v_bfe_u32 v197, v0, 4, 2
	v_add_lshl_u32 v133, v2, v7, 1
	v_and_b32_e32 v196, 15, v0
	v_lshlrev_b32_e32 v2, 4, v197
	v_lshlrev_b32_e32 v0, 2, v0
	v_lshl_or_b32 v2, v196, 6, v2
	s_lshl_b32 s4, s40, 13
	v_and_b32_e32 v0, 32, v0
	v_bitop3_b32 v4, v2, s4, v0 bitop3:0xde
	s_lshl_b32 s4, s41, 12
	v_bitop3_b32 v134, v2, s4, v0 bitop3:0xde
	v_mov_b32_e32 v0, v130
	s_waitcnt vmcnt(2)
	s_barrier
	s_add_i32 s75, s60, 0x8000
	v_lshl_add_u64 v[2:3], s[48:49], 0, v[0:1]
	v_lshl_add_u64 v[2:3], v[2:3], 0, s[38:39]
	s_mov_b32 m0, s75
	v_mov_b32_e32 v0, v131
	global_load_lds_dwordx4 v[2:3], off
	s_add_i32 s78, s60, 0xa000
	v_lshl_add_u64 v[2:3], s[48:49], 0, v[0:1]
	v_lshl_add_u64 v[2:3], v[2:3], 0, s[38:39]
	s_mov_b32 m0, s78
	s_and_b32 s4, s77, 7
	global_load_lds_dwordx4 v[2:3], off
	s_mul_i32 s4, s4, 0xc00000
	s_mul_i32 s5, s5, 0x180000
	s_lshl_b32 s74, s40, 6
	s_add_i32 s4, s4, s5
	s_add_u32 s79, s12, s4
	s_addc_u32 s82, s13, 0
	v_readlane_b32 s4, v255, 16
	s_add_u32 s4, s12, s4
	s_addc_u32 s5, s13, 0
	s_add_u32 s46, s64, s46
	s_addc_u32 s47, 0, 0
	s_add_u32 s4, s4, s46
	s_waitcnt vmcnt(2)
	s_addc_u32 s5, s5, s47
	s_add_u32 s64, s4, 0x200100
	v_mov_b32_e32 v2, 0
	s_addc_u32 s83, s5, 0
	s_mov_b32 s84, -2
	s_mov_b64 s[50:51], 0
	v_add_u32_e32 v135, 0, v4
	v_mov_b32_e32 v3, v2
	v_mov_b32_e32 v4, v2
	v_mov_b32_e32 v5, v2
	v_mov_b32_e32 v6, v2
	v_mov_b32_e32 v7, v2
	v_mov_b32_e32 v8, v2
	v_mov_b32_e32 v9, v2
	v_mov_b32_e32 v18, v2
	v_mov_b32_e32 v19, v2
	v_mov_b32_e32 v20, v2
	v_mov_b32_e32 v21, v2
	v_mov_b32_e32 v22, v2
	v_mov_b32_e32 v23, v2
	v_mov_b32_e32 v24, v2
	v_mov_b32_e32 v25, v2
	v_mov_b32_e32 v34, v2
	v_mov_b32_e32 v35, v2
	v_mov_b32_e32 v36, v2
	v_mov_b32_e32 v37, v2
	v_mov_b32_e32 v38, v2
	v_mov_b32_e32 v39, v2
	v_mov_b32_e32 v40, v2
	v_mov_b32_e32 v41, v2
	v_mov_b32_e32 v50, v2
	v_mov_b32_e32 v51, v2
	v_mov_b32_e32 v52, v2
	v_mov_b32_e32 v53, v2
	v_mov_b32_e32 v54, v2
	v_mov_b32_e32 v55, v2
	v_mov_b32_e32 v56, v2
	v_mov_b32_e32 v57, v2
	v_mov_b32_e32 v10, v2
	v_mov_b32_e32 v11, v2
	v_mov_b32_e32 v12, v2
	v_mov_b32_e32 v13, v2
	v_mov_b32_e32 v14, v2
	v_mov_b32_e32 v15, v2
	v_mov_b32_e32 v16, v2
	v_mov_b32_e32 v17, v2
	v_mov_b32_e32 v26, v2
	v_mov_b32_e32 v27, v2
	v_mov_b32_e32 v28, v2
	v_mov_b32_e32 v29, v2
	v_mov_b32_e32 v30, v2
	v_mov_b32_e32 v31, v2
	v_mov_b32_e32 v32, v2
	v_mov_b32_e32 v33, v2
	v_mov_b32_e32 v42, v2
	v_mov_b32_e32 v43, v2
	v_mov_b32_e32 v44, v2
	v_mov_b32_e32 v45, v2
	v_mov_b32_e32 v46, v2
	v_mov_b32_e32 v47, v2
	v_mov_b32_e32 v48, v2
	v_mov_b32_e32 v49, v2
	v_mov_b32_e32 v58, v2
	v_mov_b32_e32 v59, v2
	v_mov_b32_e32 v60, v2
	v_mov_b32_e32 v61, v2
	v_mov_b32_e32 v62, v2
	v_mov_b32_e32 v63, v2
	v_mov_b32_e32 v64, v2
	v_mov_b32_e32 v65, v2
	v_mov_b32_e32 v66, v2
	v_mov_b32_e32 v67, v2
	v_mov_b32_e32 v68, v2
	v_mov_b32_e32 v69, v2
	v_mov_b32_e32 v70, v2
	v_mov_b32_e32 v71, v2
	v_mov_b32_e32 v72, v2
	v_mov_b32_e32 v73, v2
	v_mov_b32_e32 v82, v2
	v_mov_b32_e32 v83, v2
	v_mov_b32_e32 v84, v2
	v_mov_b32_e32 v85, v2
	v_mov_b32_e32 v86, v2
	v_mov_b32_e32 v87, v2
	v_mov_b32_e32 v88, v2
	v_mov_b32_e32 v89, v2
	v_mov_b32_e32 v98, v2
	v_mov_b32_e32 v99, v2
	v_mov_b32_e32 v100, v2
	v_mov_b32_e32 v101, v2
	v_mov_b32_e32 v102, v2
	v_mov_b32_e32 v103, v2
	v_mov_b32_e32 v104, v2
	v_mov_b32_e32 v105, v2
	v_mov_b32_e32 v114, v2
	v_mov_b32_e32 v115, v2
	v_mov_b32_e32 v116, v2
	v_mov_b32_e32 v117, v2
	v_mov_b32_e32 v118, v2
	v_mov_b32_e32 v119, v2
	v_mov_b32_e32 v120, v2
	v_mov_b32_e32 v121, v2
	v_mov_b32_e32 v74, v2
	v_mov_b32_e32 v75, v2
	v_mov_b32_e32 v76, v2
	v_mov_b32_e32 v77, v2
	v_mov_b32_e32 v78, v2
	v_mov_b32_e32 v79, v2
	v_mov_b32_e32 v80, v2
	v_mov_b32_e32 v81, v2
	v_mov_b32_e32 v90, v2
	v_mov_b32_e32 v91, v2
	v_mov_b32_e32 v92, v2
	v_mov_b32_e32 v93, v2
	v_mov_b32_e32 v94, v2
	v_mov_b32_e32 v95, v2
	v_mov_b32_e32 v96, v2
	v_mov_b32_e32 v97, v2
	v_mov_b32_e32 v106, v2
	v_mov_b32_e32 v107, v2
	v_mov_b32_e32 v108, v2
	v_mov_b32_e32 v109, v2
	v_mov_b32_e32 v110, v2
	v_mov_b32_e32 v111, v2
	v_mov_b32_e32 v112, v2
	v_mov_b32_e32 v113, v2
	v_mov_b32_e32 v122, v2
	v_mov_b32_e32 v123, v2
	v_mov_b32_e32 v124, v2
	v_mov_b32_e32 v125, v2
	v_mov_b32_e32 v126, v2
	v_mov_b32_e32 v127, v2
	v_mov_b32_e32 v128, v2
	v_mov_b32_e32 v129, v2
	s_mov_b64 s[88:89], 0x98b0080
	s_barrier
	.p2align	6

.LBB0_868:
	s_add_u32 s58, s16, 0x100
	s_addc_u32 s59, s17, 0
	s_and_b32 s61, s2, 3
	v_lshlrev_b32_e32 v8, 1, v2
	v_lshrrev_b32_e32 v9, 2, v2
	v_and_b32_e32 v3, 3, v3
	s_mov_b32 s2, 0xffffe0
	v_and_b32_e32 v8, 24, v8
	v_and_b32_e32 v9, 4, v9
	v_and_or_b32 v2, v2, s2, v3
	v_or3_b32 v2, v2, v9, v8
	v_mul_u32_u24_e32 v2, 0xb00, v2
	v_add_lshl_u32 v124, v2, v4, 1
	v_lshlrev_b32_e32 v2, 1, v5
	v_lshrrev_b32_e32 v3, 2, v5
	v_and_b32_e32 v4, 3, v6
	v_and_b32_e32 v2, 24, v2
	v_and_b32_e32 v3, 4, v3
	v_and_or_b32 v4, v5, s2, v4
	v_or3_b32 v2, v4, v3, v2
	v_mul_u32_u24_e32 v2, 0xb00, v2
	v_bfe_u32 v158, v0, 4, 2
	v_add_lshl_u32 v125, v2, v7, 1
	v_and_b32_e32 v159, 15, v0
	v_lshlrev_b32_e32 v2, 4, v158
	v_lshlrev_b32_e32 v0, 2, v0
	v_lshl_or_b32 v2, v159, 6, v2
	s_lshl_b32 s2, s40, 13
	v_and_b32_e32 v0, 32, v0
	v_bitop3_b32 v4, v2, s2, v0 bitop3:0xde
	s_lshl_b32 s2, s61, 12
	v_bitop3_b32 v126, v2, s2, v0 bitop3:0xde
	v_mov_b32_e32 v0, v122
	s_waitcnt vmcnt(2)
	s_barrier
	s_add_i32 s64, s41, 0x8000
	v_lshl_add_u64 v[2:3], s[10:11], 0, v[0:1]
	v_lshl_add_u64 v[2:3], v[2:3], 0, s[38:39]
	s_mov_b32 m0, s64
	v_mov_b32_e32 v0, v123
	global_load_lds_dwordx4 v[2:3], off
	s_add_i32 s65, s41, 0xa000
	v_lshl_add_u64 v[2:3], s[10:11], 0, v[0:1]
	v_lshl_add_u64 v[2:3], v[2:3], 0, s[38:39]
	s_mov_b32 m0, s65
	s_lshl_b32 s51, s40, 6
	global_load_lds_dwordx4 v[2:3], off
	s_waitcnt vmcnt(2)
	v_mov_b32_e32 v2, 0
	s_mov_b32 s68, -2
	s_mov_b64 s[2:3], 0
	v_add_u32_e32 v127, 0, v4
	v_mov_b32_e32 v3, v2
	v_mov_b32_e32 v4, v2
	v_mov_b32_e32 v5, v2
	v_mov_b32_e32 v6, v2
	v_mov_b32_e32 v7, v2
	v_mov_b32_e32 v8, v2
	v_mov_b32_e32 v9, v2
	v_mov_b32_e32 v18, v2
	v_mov_b32_e32 v19, v2
	v_mov_b32_e32 v20, v2
	v_mov_b32_e32 v21, v2
	v_mov_b32_e32 v22, v2
	v_mov_b32_e32 v23, v2
	v_mov_b32_e32 v24, v2
	v_mov_b32_e32 v25, v2
	v_mov_b32_e32 v34, v2
	v_mov_b32_e32 v35, v2
	v_mov_b32_e32 v36, v2
	v_mov_b32_e32 v37, v2
	v_mov_b32_e32 v38, v2
	v_mov_b32_e32 v39, v2
	v_mov_b32_e32 v40, v2
	v_mov_b32_e32 v41, v2
	v_mov_b32_e32 v50, v2
	v_mov_b32_e32 v51, v2
	v_mov_b32_e32 v52, v2
	v_mov_b32_e32 v53, v2
	v_mov_b32_e32 v54, v2
	v_mov_b32_e32 v55, v2
	v_mov_b32_e32 v56, v2
	v_mov_b32_e32 v57, v2
	v_mov_b32_e32 v10, v2
	v_mov_b32_e32 v11, v2
	v_mov_b32_e32 v12, v2
	v_mov_b32_e32 v13, v2
	v_mov_b32_e32 v14, v2
	v_mov_b32_e32 v15, v2
	v_mov_b32_e32 v16, v2
	v_mov_b32_e32 v17, v2
	v_mov_b32_e32 v26, v2
	v_mov_b32_e32 v27, v2
	v_mov_b32_e32 v28, v2
	v_mov_b32_e32 v29, v2
	v_mov_b32_e32 v30, v2
	v_mov_b32_e32 v31, v2
	v_mov_b32_e32 v32, v2
	v_mov_b32_e32 v33, v2
	v_mov_b32_e32 v42, v2
	v_mov_b32_e32 v43, v2
	v_mov_b32_e32 v44, v2
	v_mov_b32_e32 v45, v2
	v_mov_b32_e32 v46, v2
	v_mov_b32_e32 v47, v2
	v_mov_b32_e32 v48, v2
	v_mov_b32_e32 v49, v2
	v_mov_b32_e32 v58, v2
	v_mov_b32_e32 v59, v2
	v_mov_b32_e32 v60, v2
	v_mov_b32_e32 v61, v2
	v_mov_b32_e32 v62, v2
	v_mov_b32_e32 v63, v2
	v_mov_b32_e32 v64, v2
	v_mov_b32_e32 v65, v2
	v_mov_b32_e32 v66, v2
	v_mov_b32_e32 v67, v2
	v_mov_b32_e32 v68, v2
	v_mov_b32_e32 v69, v2
	v_mov_b32_e32 v70, v2
	v_mov_b32_e32 v71, v2
	v_mov_b32_e32 v72, v2
	v_mov_b32_e32 v73, v2
	v_mov_b32_e32 v82, v2
	v_mov_b32_e32 v83, v2
	v_mov_b32_e32 v84, v2
	v_mov_b32_e32 v85, v2
	v_mov_b32_e32 v86, v2
	v_mov_b32_e32 v87, v2
	v_mov_b32_e32 v88, v2
	v_mov_b32_e32 v89, v2
	v_mov_b32_e32 v98, v2
	v_mov_b32_e32 v99, v2
	v_mov_b32_e32 v100, v2
	v_mov_b32_e32 v101, v2
	v_mov_b32_e32 v102, v2
	v_mov_b32_e32 v103, v2
	v_mov_b32_e32 v104, v2
	v_mov_b32_e32 v105, v2
	v_mov_b32_e32 v114, v2
	v_mov_b32_e32 v115, v2
	v_mov_b32_e32 v116, v2
	v_mov_b32_e32 v117, v2
	v_mov_b32_e32 v118, v2
	v_mov_b32_e32 v119, v2
	v_mov_b32_e32 v120, v2
	v_mov_b32_e32 v121, v2
	v_mov_b32_e32 v74, v2
	v_mov_b32_e32 v75, v2
	v_mov_b32_e32 v76, v2
	v_mov_b32_e32 v77, v2
	v_mov_b32_e32 v78, v2
	v_mov_b32_e32 v79, v2
	v_mov_b32_e32 v80, v2
	v_mov_b32_e32 v81, v2
	v_mov_b32_e32 v90, v2
	v_mov_b32_e32 v91, v2
	v_mov_b32_e32 v92, v2
	v_mov_b32_e32 v93, v2
	v_mov_b32_e32 v94, v2
	v_mov_b32_e32 v95, v2
	v_mov_b32_e32 v96, v2
	v_mov_b32_e32 v97, v2
	v_mov_b32_e32 v106, v2
	v_mov_b32_e32 v107, v2
	v_mov_b32_e32 v108, v2
	v_mov_b32_e32 v109, v2
	v_mov_b32_e32 v110, v2
	v_mov_b32_e32 v111, v2
	v_mov_b32_e32 v112, v2
	v_mov_b32_e32 v113, v2
	v_mov_b32_e32 v134, v2
	v_mov_b32_e32 v135, v2
	v_mov_b32_e32 v136, v2
	v_mov_b32_e32 v137, v2
	v_mov_b32_e32 v138, v2
	v_mov_b32_e32 v139, v2
	v_mov_b32_e32 v140, v2
	v_mov_b32_e32 v141, v2
	s_barrier
	.p2align	6

.LBB0_952:
	s_add_u32 s43, s6, 0x100
	s_addc_u32 s46, s7, 0
	s_and_b32 s23, s2, 3
	v_lshlrev_b32_e32 v8, 1, v2
	v_lshrrev_b32_e32 v9, 2, v2
	v_and_b32_e32 v3, 3, v3
	s_mov_b32 s2, 0xffffe0
	v_and_b32_e32 v8, 24, v8
	v_and_b32_e32 v9, 4, v9
	v_and_or_b32 v2, v2, s2, v3
	v_or3_b32 v2, v2, v9, v8
	v_mul_u32_u24_e32 v2, 0xb00, v2
	v_add_lshl_u32 v133, v2, v4, 1
	v_lshlrev_b32_e32 v2, 1, v5
	v_lshrrev_b32_e32 v3, 2, v5
	v_and_b32_e32 v4, 3, v6
	v_and_b32_e32 v2, 24, v2
	v_and_b32_e32 v3, 4, v3
	v_and_or_b32 v4, v5, s2, v4
	v_or3_b32 v2, v4, v3, v2
	v_mul_u32_u24_e32 v2, 0xb00, v2
	v_bfe_u32 v240, v0, 4, 2
	v_add_lshl_u32 v134, v2, v7, 1
	v_and_b32_e32 v132, 15, v0
	v_lshlrev_b32_e32 v2, 4, v240
	v_lshlrev_b32_e32 v0, 2, v0
	v_lshl_or_b32 v2, v132, 6, v2
	s_lshl_b32 s2, s3, 13
	v_and_b32_e32 v0, 32, v0
	v_bitop3_b32 v4, v2, s2, v0 bitop3:0xde
	s_lshl_b32 s2, s23, 12
	v_bitop3_b32 v135, v2, s2, v0 bitop3:0xde
	v_mov_b32_e32 v0, v130
	s_waitcnt vmcnt(2)
	s_barrier
	s_add_i32 s48, s37, 0x8000
	v_lshl_add_u64 v[2:3], s[4:5], 0, v[0:1]
	v_lshl_add_u64 v[2:3], v[2:3], 0, s[38:39]
	s_mov_b32 m0, s48
	v_mov_b32_e32 v0, v131
	global_load_lds_dwordx4 v[2:3], off
	s_add_i32 s49, s37, 0xa000
	v_lshl_add_u64 v[2:3], s[4:5], 0, v[0:1]
	v_lshl_add_u64 v[2:3], v[2:3], 0, s[38:39]
	s_mov_b32 m0, s49
	s_lshl_b32 s47, s3, 6
	global_load_lds_dwordx4 v[2:3], off
	s_waitcnt vmcnt(2)
	v_mov_b32_e32 v2, 0
	s_mov_b32 s50, -2
	s_mov_b64 s[2:3], 0
	v_add_u32_e32 v136, 0, v4
	v_mov_b32_e32 v3, v2
	v_mov_b32_e32 v4, v2
	v_mov_b32_e32 v5, v2
	v_mov_b32_e32 v6, v2
	v_mov_b32_e32 v7, v2
	v_mov_b32_e32 v8, v2
	v_mov_b32_e32 v9, v2
	v_mov_b32_e32 v18, v2
	v_mov_b32_e32 v19, v2
	v_mov_b32_e32 v20, v2
	v_mov_b32_e32 v21, v2
	v_mov_b32_e32 v22, v2
	v_mov_b32_e32 v23, v2
	v_mov_b32_e32 v24, v2
	v_mov_b32_e32 v25, v2
	v_mov_b32_e32 v34, v2
	v_mov_b32_e32 v35, v2
	v_mov_b32_e32 v36, v2
	v_mov_b32_e32 v37, v2
	v_mov_b32_e32 v38, v2
	v_mov_b32_e32 v39, v2
	v_mov_b32_e32 v40, v2
	v_mov_b32_e32 v41, v2
	v_mov_b32_e32 v50, v2
	v_mov_b32_e32 v51, v2
	v_mov_b32_e32 v52, v2
	v_mov_b32_e32 v53, v2
	v_mov_b32_e32 v54, v2
	v_mov_b32_e32 v55, v2
	v_mov_b32_e32 v56, v2
	v_mov_b32_e32 v57, v2
	v_mov_b32_e32 v10, v2
	v_mov_b32_e32 v11, v2
	v_mov_b32_e32 v12, v2
	v_mov_b32_e32 v13, v2
	v_mov_b32_e32 v14, v2
	v_mov_b32_e32 v15, v2
	v_mov_b32_e32 v16, v2
	v_mov_b32_e32 v17, v2
	v_mov_b32_e32 v26, v2
	v_mov_b32_e32 v27, v2
	v_mov_b32_e32 v28, v2
	v_mov_b32_e32 v29, v2
	v_mov_b32_e32 v30, v2
	v_mov_b32_e32 v31, v2
	v_mov_b32_e32 v32, v2
	v_mov_b32_e32 v33, v2
	v_mov_b32_e32 v42, v2
	v_mov_b32_e32 v43, v2
	v_mov_b32_e32 v44, v2
	v_mov_b32_e32 v45, v2
	v_mov_b32_e32 v46, v2
	v_mov_b32_e32 v47, v2
	v_mov_b32_e32 v48, v2
	v_mov_b32_e32 v49, v2
	v_mov_b32_e32 v58, v2
	v_mov_b32_e32 v59, v2
	v_mov_b32_e32 v60, v2
	v_mov_b32_e32 v61, v2
	v_mov_b32_e32 v62, v2
	v_mov_b32_e32 v63, v2
	v_mov_b32_e32 v64, v2
	v_mov_b32_e32 v65, v2
	v_mov_b32_e32 v66, v2
	v_mov_b32_e32 v67, v2
	v_mov_b32_e32 v68, v2
	v_mov_b32_e32 v69, v2
	v_mov_b32_e32 v70, v2
	v_mov_b32_e32 v71, v2
	v_mov_b32_e32 v72, v2
	v_mov_b32_e32 v73, v2
	v_mov_b32_e32 v82, v2
	v_mov_b32_e32 v83, v2
	v_mov_b32_e32 v84, v2
	v_mov_b32_e32 v85, v2
	v_mov_b32_e32 v86, v2
	v_mov_b32_e32 v87, v2
	v_mov_b32_e32 v88, v2
	v_mov_b32_e32 v89, v2
	v_mov_b32_e32 v98, v2
	v_mov_b32_e32 v99, v2
	v_mov_b32_e32 v100, v2
	v_mov_b32_e32 v101, v2
	v_mov_b32_e32 v102, v2
	v_mov_b32_e32 v103, v2
	v_mov_b32_e32 v104, v2
	v_mov_b32_e32 v105, v2
	v_mov_b32_e32 v114, v2
	v_mov_b32_e32 v115, v2
	v_mov_b32_e32 v116, v2
	v_mov_b32_e32 v117, v2
	v_mov_b32_e32 v118, v2
	v_mov_b32_e32 v119, v2
	v_mov_b32_e32 v120, v2
	v_mov_b32_e32 v121, v2
	v_mov_b32_e32 v74, v2
	v_mov_b32_e32 v75, v2
	v_mov_b32_e32 v76, v2
	v_mov_b32_e32 v77, v2
	v_mov_b32_e32 v78, v2
	v_mov_b32_e32 v79, v2
	v_mov_b32_e32 v80, v2
	v_mov_b32_e32 v81, v2
	v_mov_b32_e32 v90, v2
	v_mov_b32_e32 v91, v2
	v_mov_b32_e32 v92, v2
	v_mov_b32_e32 v93, v2
	v_mov_b32_e32 v94, v2
	v_mov_b32_e32 v95, v2
	v_mov_b32_e32 v96, v2
	v_mov_b32_e32 v97, v2
	v_mov_b32_e32 v106, v2
	v_mov_b32_e32 v107, v2
	v_mov_b32_e32 v108, v2
	v_mov_b32_e32 v109, v2
	v_mov_b32_e32 v110, v2
	v_mov_b32_e32 v111, v2
	v_mov_b32_e32 v112, v2
	v_mov_b32_e32 v113, v2
	v_mov_b32_e32 v122, v2
	v_mov_b32_e32 v123, v2
	v_mov_b32_e32 v124, v2
	v_mov_b32_e32 v125, v2
	v_mov_b32_e32 v126, v2
	v_mov_b32_e32 v127, v2
	v_mov_b32_e32 v128, v2
	v_mov_b32_e32 v129, v2
	s_barrier
	.p2align	6

.LBB0_1087:
	s_add_u32 s2, s6, 0x40080
	s_addc_u32 s3, s7, 0
	s_add_u32 s8, s8, 0x100
	s_addc_u32 s9, s9, 0
	s_mov_b32 s22, -2
	s_add_u32 s4, s2, 0xfffc0080
	s_addc_u32 s5, s3, -1
	s_add_i32 s23, 0, 0x10000
	s_cmp_eq_u32 s22, 12
	s_cselect_b32 s5, s49, s5
	s_cselect_b32 s4, s48, s4
	s_waitcnt vmcnt(0)
	v_add_u32_e32 v0, s23, v145
	s_cselect_b32 s7, s97, s9
	s_cselect_b32 s6, s96, s8
	s_add_i32 s25, 0, 0x14000
	ds_read_b128 v[146:149], v0
	ds_read_b128 v[152:155], v0 offset:1024
	ds_read_b128 v[156:159], v0 offset:2048
	ds_read_b128 v[160:163], v0 offset:3072
	ds_read_b128 v[164:167], v0 offset:16384
	ds_read_b128 v[168:171], v0 offset:17408
	ds_read_b128 v[172:175], v0 offset:18432
	ds_read_b128 v[176:179], v0 offset:19456
	ds_read_b128 v[180:183], v150
	ds_read_b128 v[184:187], v150 offset:1024
	ds_read_b128 v[188:191], v150 offset:2048
	ds_read_b128 v[192:195], v150 offset:3072
	ds_read_b128 v[196:199], v150 offset:4096
	ds_read_b128 v[200:203], v150 offset:5120
	ds_read_b128 v[204:207], v150 offset:6144
	ds_read_b128 v[208:211], v150 offset:7168
	s_add_i32 m0, s60, 0xc000
	s_nop 0
	global_load_lds_dwordx4 v131, s[2:3]
	s_add_i32 m0, s60, 0xe000
	s_nop 0
	global_load_lds_dwordx4 v133, s[2:3]
	s_waitcnt vmcnt(8)
	s_waitcnt lgkmcnt(0)
	s_barrier
	s_setprio 1
	s_waitcnt lgkmcnt(0)
	v_mfma_f32_16x16x32_bf16 v[126:129], v[146:149], v[180:183], 0
	v_mfma_f32_16x16x32_bf16 v[122:125], v[156:159], v[180:183], 0
	v_mfma_f32_16x16x32_bf16 v[110:113], v[146:149], v[188:191], 0
	v_mfma_f32_16x16x32_bf16 v[106:109], v[156:159], v[188:191], 0
	v_mfma_f32_16x16x32_bf16 v[94:97], v[146:149], v[196:199], 0
	v_mfma_f32_16x16x32_bf16 v[90:93], v[156:159], v[196:199], 0
	v_mfma_f32_16x16x32_bf16 v[78:81], v[146:149], v[204:207], 0
	v_mfma_f32_16x16x32_bf16 v[74:77], v[156:159], v[204:207], 0
	v_mfma_f32_16x16x32_bf16 v[126:129], v[152:155], v[184:187], v[126:129]
	v_mfma_f32_16x16x32_bf16 v[122:125], v[160:163], v[184:187], v[122:125]
	v_mfma_f32_16x16x32_bf16 v[110:113], v[152:155], v[192:195], v[110:113]
	v_mfma_f32_16x16x32_bf16 v[106:109], v[160:163], v[192:195], v[106:109]
	v_mfma_f32_16x16x32_bf16 v[94:97], v[152:155], v[200:203], v[94:97]
	v_mfma_f32_16x16x32_bf16 v[90:93], v[160:163], v[200:203], v[90:93]
	v_mfma_f32_16x16x32_bf16 v[78:81], v[152:155], v[208:211], v[78:81]
	v_mfma_f32_16x16x32_bf16 v[74:77], v[160:163], v[208:211], v[74:77]
	s_setprio 0
	s_setprio 1
	v_mfma_f32_16x16x32_bf16 v[118:121], v[164:167], v[180:183], 0
	v_mfma_f32_16x16x32_bf16 v[114:117], v[172:175], v[180:183], 0
	v_mfma_f32_16x16x32_bf16 v[102:105], v[164:167], v[188:191], 0
	v_mfma_f32_16x16x32_bf16 v[98:101], v[172:175], v[188:191], 0
	v_mfma_f32_16x16x32_bf16 v[86:89], v[164:167], v[196:199], 0
	v_mfma_f32_16x16x32_bf16 v[82:85], v[172:175], v[196:199], 0
	v_mfma_f32_16x16x32_bf16 v[70:73], v[164:167], v[204:207], 0
	v_mfma_f32_16x16x32_bf16 v[66:69], v[172:175], v[204:207], 0
	v_mfma_f32_16x16x32_bf16 v[118:121], v[168:171], v[184:187], v[118:121]
	v_mfma_f32_16x16x32_bf16 v[114:117], v[176:179], v[184:187], v[114:117]
	v_mfma_f32_16x16x32_bf16 v[102:105], v[168:171], v[192:195], v[102:105]
	v_mfma_f32_16x16x32_bf16 v[98:101], v[176:179], v[192:195], v[98:101]
	v_mfma_f32_16x16x32_bf16 v[86:89], v[168:171], v[200:203], v[86:89]
	v_mfma_f32_16x16x32_bf16 v[82:85], v[176:179], v[200:203], v[82:85]
	v_mfma_f32_16x16x32_bf16 v[70:73], v[168:171], v[208:211], v[70:73]
	v_mfma_f32_16x16x32_bf16 v[66:69], v[176:179], v[208:211], v[66:69]
	s_setprio 0
	s_barrier
	s_add_i32 s23, s23, s42
	ds_read_b128 v[180:183], v150 offset:16384
	ds_read_b128 v[184:187], v150 offset:17408
	ds_read_b128 v[188:191], v150 offset:18432
	ds_read_b128 v[192:195], v150 offset:19456
	ds_read_b128 v[196:199], v150 offset:20480
	ds_read_b128 v[200:203], v150 offset:21504
	ds_read_b128 v[204:207], v150 offset:22528
	ds_read_b128 v[208:211], v150 offset:23552
	s_mov_b32 m0, s23
	s_nop 0
	global_load_lds_dwordx4 v137, s[6:7]
	s_add_i32 m0, s23, 0x2000
	s_add_u32 s46, s6, 0x40000
	global_load_lds_dwordx4 v139, s[6:7]
	s_addc_u32 s47, s7, 0
	s_add_i32 s23, s25, s42
	s_mov_b32 m0, s23
	s_nop 0
	global_load_lds_dwordx4 v137, s[46:47]
	s_add_i32 m0, s23, 0x2000
	s_nop 0
	global_load_lds_dwordx4 v139, s[46:47]
	s_mov_b32 m0, s60
	s_nop 0
	global_load_lds_dwordx4 v131, s[4:5]
	s_mov_b32 m0, s61
	s_nop 0
	global_load_lds_dwordx4 v133, s[4:5]
	s_waitcnt vmcnt(8)
	s_waitcnt lgkmcnt(0)
	s_barrier
	s_setprio 1
	s_waitcnt lgkmcnt(0)
	v_mfma_f32_16x16x32_bf16 v[62:65], v[146:149], v[180:183], 0
	v_mfma_f32_16x16x32_bf16 v[58:61], v[156:159], v[180:183], 0
	v_mfma_f32_16x16x32_bf16 v[46:49], v[146:149], v[188:191], 0
	v_mfma_f32_16x16x32_bf16 v[42:45], v[156:159], v[188:191], 0
	v_mfma_f32_16x16x32_bf16 v[30:33], v[146:149], v[196:199], 0
	v_mfma_f32_16x16x32_bf16 v[26:29], v[156:159], v[196:199], 0
	v_mfma_f32_16x16x32_bf16 v[14:17], v[146:149], v[204:207], 0
	v_mfma_f32_16x16x32_bf16 v[10:13], v[156:159], v[204:207], 0
	v_mfma_f32_16x16x32_bf16 v[62:65], v[152:155], v[184:187], v[62:65]
	v_mfma_f32_16x16x32_bf16 v[58:61], v[160:163], v[184:187], v[58:61]
	v_mfma_f32_16x16x32_bf16 v[46:49], v[152:155], v[192:195], v[46:49]
	v_mfma_f32_16x16x32_bf16 v[42:45], v[160:163], v[192:195], v[42:45]
	v_mfma_f32_16x16x32_bf16 v[30:33], v[152:155], v[200:203], v[30:33]
	v_mfma_f32_16x16x32_bf16 v[26:29], v[160:163], v[200:203], v[26:29]
	v_mfma_f32_16x16x32_bf16 v[14:17], v[152:155], v[208:211], v[14:17]
	v_mfma_f32_16x16x32_bf16 v[10:13], v[160:163], v[208:211], v[10:13]
	s_setprio 0
	s_setprio 1
	v_mfma_f32_16x16x32_bf16 v[54:57], v[164:167], v[180:183], 0
	v_mfma_f32_16x16x32_bf16 v[50:53], v[172:175], v[180:183], 0
	v_mfma_f32_16x16x32_bf16 v[38:41], v[164:167], v[188:191], 0
	v_mfma_f32_16x16x32_bf16 v[34:37], v[172:175], v[188:191], 0
	v_mfma_f32_16x16x32_bf16 v[22:25], v[164:167], v[196:199], 0
	v_mfma_f32_16x16x32_bf16 v[18:21], v[172:175], v[196:199], 0
	v_mfma_f32_16x16x32_bf16 v[6:9], v[164:167], v[204:207], 0
	v_mfma_f32_16x16x32_bf16 v[2:5], v[172:175], v[204:207], 0
	v_mfma_f32_16x16x32_bf16 v[54:57], v[168:171], v[184:187], v[54:57]
	v_mfma_f32_16x16x32_bf16 v[50:53], v[176:179], v[184:187], v[50:53]
	v_mfma_f32_16x16x32_bf16 v[38:41], v[168:171], v[192:195], v[38:41]
	v_mfma_f32_16x16x32_bf16 v[34:37], v[176:179], v[192:195], v[34:37]
	v_mfma_f32_16x16x32_bf16 v[22:25], v[168:171], v[200:203], v[22:25]
	v_mfma_f32_16x16x32_bf16 v[18:21], v[176:179], v[200:203], v[18:21]
	v_mfma_f32_16x16x32_bf16 v[6:9], v[168:171], v[208:211], v[6:9]
	v_mfma_f32_16x16x32_bf16 v[2:5], v[176:179], v[208:211], v[2:5]
	s_setprio 0
	s_barrier
	s_add_i32 s23, 0, 0x18000
	s_add_i32 s25, 0, 0x1c000
	ds_read_b128 v[146:149], v0 offset:32768
	ds_read_b128 v[152:155], v0 offset:33792
	ds_read_b128 v[156:159], v0 offset:34816
	ds_read_b128 v[160:163], v0 offset:35840
	ds_read_b128 v[164:167], v0 offset:49152
	ds_read_b128 v[168:171], v0 offset:50176
	ds_read_b128 v[172:175], v0 offset:51200
	ds_read_b128 v[176:179], v0 offset:52224
	s_add_u32 s46, s4, 0x40000
	s_mov_b32 m0, s66
	ds_read_b128 v[180:183], v150 offset:32768
	ds_read_b128 v[184:187], v150 offset:33792
	ds_read_b128 v[188:191], v150 offset:34816
	ds_read_b128 v[192:195], v150 offset:35840
	ds_read_b128 v[196:199], v150 offset:36864
	ds_read_b128 v[200:203], v150 offset:37888
	ds_read_b128 v[204:207], v150 offset:38912
	ds_read_b128 v[208:211], v150 offset:39936
	s_addc_u32 s47, s5, 0
	s_nop 0
	global_load_lds_dwordx4 v131, s[46:47]
	s_mov_b32 m0, s67
	s_nop 0
	global_load_lds_dwordx4 v133, s[46:47]
	s_waitcnt vmcnt(8)
	s_waitcnt lgkmcnt(0)
	s_barrier
	s_setprio 1
	s_waitcnt lgkmcnt(0)
	v_mfma_f32_16x16x32_bf16 v[126:129], v[146:149], v[180:183], v[126:129]
	v_mfma_f32_16x16x32_bf16 v[122:125], v[156:159], v[180:183], v[122:125]
	v_mfma_f32_16x16x32_bf16 v[110:113], v[146:149], v[188:191], v[110:113]
	v_mfma_f32_16x16x32_bf16 v[106:109], v[156:159], v[188:191], v[106:109]
	v_mfma_f32_16x16x32_bf16 v[94:97], v[146:149], v[196:199], v[94:97]
	v_mfma_f32_16x16x32_bf16 v[90:93], v[156:159], v[196:199], v[90:93]
	v_mfma_f32_16x16x32_bf16 v[78:81], v[146:149], v[204:207], v[78:81]
	v_mfma_f32_16x16x32_bf16 v[74:77], v[156:159], v[204:207], v[74:77]
	v_mfma_f32_16x16x32_bf16 v[126:129], v[152:155], v[184:187], v[126:129]
	v_mfma_f32_16x16x32_bf16 v[122:125], v[160:163], v[184:187], v[122:125]
	v_mfma_f32_16x16x32_bf16 v[110:113], v[152:155], v[192:195], v[110:113]
	v_mfma_f32_16x16x32_bf16 v[106:109], v[160:163], v[192:195], v[106:109]
	v_mfma_f32_16x16x32_bf16 v[94:97], v[152:155], v[200:203], v[94:97]
	v_mfma_f32_16x16x32_bf16 v[90:93], v[160:163], v[200:203], v[90:93]
	v_mfma_f32_16x16x32_bf16 v[78:81], v[152:155], v[208:211], v[78:81]
	v_mfma_f32_16x16x32_bf16 v[74:77], v[160:163], v[208:211], v[74:77]
	s_setprio 0
	s_setprio 1
	v_mfma_f32_16x16x32_bf16 v[118:121], v[164:167], v[180:183], v[118:121]
	v_mfma_f32_16x16x32_bf16 v[114:117], v[172:175], v[180:183], v[114:117]
	v_mfma_f32_16x16x32_bf16 v[102:105], v[164:167], v[188:191], v[102:105]
	v_mfma_f32_16x16x32_bf16 v[98:101], v[172:175], v[188:191], v[98:101]
	v_mfma_f32_16x16x32_bf16 v[86:89], v[164:167], v[196:199], v[86:89]
	v_mfma_f32_16x16x32_bf16 v[82:85], v[172:175], v[196:199], v[82:85]
	v_mfma_f32_16x16x32_bf16 v[70:73], v[164:167], v[204:207], v[70:73]
	v_mfma_f32_16x16x32_bf16 v[66:69], v[172:175], v[204:207], v[66:69]
	v_mfma_f32_16x16x32_bf16 v[118:121], v[168:171], v[184:187], v[118:121]
	v_mfma_f32_16x16x32_bf16 v[114:117], v[176:179], v[184:187], v[114:117]
	v_mfma_f32_16x16x32_bf16 v[102:105], v[168:171], v[192:195], v[102:105]
	v_mfma_f32_16x16x32_bf16 v[98:101], v[176:179], v[192:195], v[98:101]
	v_mfma_f32_16x16x32_bf16 v[86:89], v[168:171], v[200:203], v[86:89]
	v_mfma_f32_16x16x32_bf16 v[82:85], v[176:179], v[200:203], v[82:85]
	v_mfma_f32_16x16x32_bf16 v[70:73], v[168:171], v[208:211], v[70:73]
	v_mfma_f32_16x16x32_bf16 v[66:69], v[176:179], v[208:211], v[66:69]
	s_setprio 0
	s_barrier
	ds_read_b128 v[180:183], v150 offset:49152
	ds_read_b128 v[184:187], v150 offset:50176
	ds_read_b128 v[188:191], v150 offset:51200
	ds_read_b128 v[192:195], v150 offset:52224
	ds_read_b128 v[196:199], v150 offset:53248
	ds_read_b128 v[200:203], v150 offset:54272
	ds_read_b128 v[204:207], v150 offset:55296
	ds_read_b128 v[208:211], v150 offset:56320
	s_add_i32 s23, s23, s42
	s_add_u32 s100, s6, s38
	s_addc_u32 s101, s7, s39
	s_mov_b32 m0, s23
	s_nop 0
	global_load_lds_dwordx4 v137, s[100:101]
	s_add_i32 m0, s23, 0x2000
	s_nop 0
	s_add_u32 s6, s6, 0x40080
	s_addc_u32 s7, s7, 0
	s_add_i32 s23, s25, s42
	global_load_lds_dwordx4 v139, s[100:101]
	s_mov_b32 m0, s23
	s_nop 0
	global_load_lds_dwordx4 v137, s[6:7]
	s_add_i32 m0, s23, 0x2000
	s_nop 0
	global_load_lds_dwordx4 v139, s[6:7]
	s_mov_b32 m0, s70
	s_add_u32 s100, s4, s38
	s_addc_u32 s101, s5, s39
	v_mov_b32_e32 v0, v133
	global_load_lds_dwordx4 v131, s[100:101]
	s_mov_b32 m0, s71
	s_nop 0
	global_load_lds_dwordx4 v133, s[100:101]
	s_waitcnt vmcnt(8)
	s_waitcnt lgkmcnt(0)
	s_barrier
	s_setprio 1
	s_waitcnt lgkmcnt(0)
	v_mfma_f32_16x16x32_bf16 v[62:65], v[146:149], v[180:183], v[62:65]
	v_mfma_f32_16x16x32_bf16 v[58:61], v[156:159], v[180:183], v[58:61]
	v_mfma_f32_16x16x32_bf16 v[46:49], v[146:149], v[188:191], v[46:49]
	v_mfma_f32_16x16x32_bf16 v[42:45], v[156:159], v[188:191], v[42:45]
	v_mfma_f32_16x16x32_bf16 v[30:33], v[146:149], v[196:199], v[30:33]
	v_mfma_f32_16x16x32_bf16 v[26:29], v[156:159], v[196:199], v[26:29]
	v_mfma_f32_16x16x32_bf16 v[14:17], v[146:149], v[204:207], v[14:17]
	v_mfma_f32_16x16x32_bf16 v[10:13], v[156:159], v[204:207], v[10:13]
	v_mfma_f32_16x16x32_bf16 v[62:65], v[152:155], v[184:187], v[62:65]
	v_mfma_f32_16x16x32_bf16 v[58:61], v[160:163], v[184:187], v[58:61]
	v_mfma_f32_16x16x32_bf16 v[46:49], v[152:155], v[192:195], v[46:49]
	v_mfma_f32_16x16x32_bf16 v[42:45], v[160:163], v[192:195], v[42:45]
	v_mfma_f32_16x16x32_bf16 v[30:33], v[152:155], v[200:203], v[30:33]
	v_mfma_f32_16x16x32_bf16 v[26:29], v[160:163], v[200:203], v[26:29]
	v_mfma_f32_16x16x32_bf16 v[14:17], v[152:155], v[208:211], v[14:17]
	v_mfma_f32_16x16x32_bf16 v[10:13], v[160:163], v[208:211], v[10:13]
	s_setprio 0
	s_setprio 1
	v_mfma_f32_16x16x32_bf16 v[54:57], v[164:167], v[180:183], v[54:57]
	v_mfma_f32_16x16x32_bf16 v[50:53], v[172:175], v[180:183], v[50:53]
	v_mfma_f32_16x16x32_bf16 v[38:41], v[164:167], v[188:191], v[38:41]
	v_mfma_f32_16x16x32_bf16 v[34:37], v[172:175], v[188:191], v[34:37]
	v_mfma_f32_16x16x32_bf16 v[22:25], v[164:167], v[196:199], v[22:25]
	v_mfma_f32_16x16x32_bf16 v[18:21], v[172:175], v[196:199], v[18:21]
	v_mfma_f32_16x16x32_bf16 v[6:9], v[164:167], v[204:207], v[6:9]
	v_mfma_f32_16x16x32_bf16 v[2:5], v[172:175], v[204:207], v[2:5]
	v_mfma_f32_16x16x32_bf16 v[54:57], v[168:171], v[184:187], v[54:57]
	v_mfma_f32_16x16x32_bf16 v[50:53], v[176:179], v[184:187], v[50:53]
	v_mfma_f32_16x16x32_bf16 v[38:41], v[168:171], v[192:195], v[38:41]
	v_mfma_f32_16x16x32_bf16 v[34:37], v[176:179], v[192:195], v[34:37]
	v_mfma_f32_16x16x32_bf16 v[22:25], v[168:171], v[200:203], v[22:25]
	v_mfma_f32_16x16x32_bf16 v[18:21], v[176:179], v[200:203], v[18:21]
	v_mfma_f32_16x16x32_bf16 v[6:9], v[168:171], v[208:211], v[6:9]
	v_mfma_f32_16x16x32_bf16 v[2:5], v[176:179], v[208:211], v[2:5]
	s_setprio 0
	s_barrier
	s_add_i32 s22, s22, 2
	s_add_u32 s2, s2, 0x100
	s_addc_u32 s3, s3, 0
	s_add_u32 s8, s8, 0x100
	s_addc_u32 s9, s9, 0
	s_cmp_gt_u32 s22, 13
	s_cbranch_scc0 .LBB0_1088
	s_branch .Lpeel_exit_1088
	.p2align	6

.LBB0_1314:
	v_lshlrev_b32_e32 v0, 1, v216
	v_and_b32_e32 v223, 32, v0
	v_lshrrev_b32_e32 v0, 2, v216
	v_and_or_b32 v0, v0, 3, v221
	v_lshlrev_b32_e32 v222, 6, v0
	v_add_u32_e32 v0, 0, v223
	v_add3_u32 v240, v0, v220, v222
	v_max3_f32 v0, v2, v3, v18
	v_max3_f32 v34, v4, v5, v19
	s_lshl_b32 s71, s24, 8
	v_max3_f32 v0, v0, v20, v21
	v_max3_f32 v34, v34, v8, v9
	s_and_b32 s17, s17, 0x3fffffc0
	v_max3_f32 v0, v0, v6, v7
	v_max3_f32 v34, v34, v24, v25
	s_add_i32 s76, s71, 0x100
	v_max3_f32 v0, v0, v22, v23
	v_max3_f32 v34, v34, v12, v13
	s_lshl_b32 s17, s17, 2
	v_max3_f32 v0, v0, v10, v11
	v_max3_f32 v34, v34, v28, v29
	s_add_i32 s17, s17, 0
	v_max3_f32 v0, v0, v26, v27
	v_max3_f32 v34, v34, v16, v17
	s_lshr_b32 s77, s76, 6
	v_max3_f32 v0, v0, v14, v15
	v_max3_f32 v34, v34, v32, v33
	s_mov_b64 s[22:23], 0x30000
	v_max3_f32 v0, v0, v30, v31
	s_cmp_lg_u32 0, -1
	v_max_f32_e32 v0, v0, v34
	s_mov_b32 s50, 1
	v_mov_b32_e32 v34, v0
	s_nop 1
	v_permlane32_swap_b32_e32 v0, v34
	v_max_f32_e32 v0, v0, v34
	s_mov_b32 s25, 0
	v_add_f32_e32 v229, v1, v0
	v_sub_f32_e32 v2, v2, v0
	v_sub_f32_e32 v3, v3, v0
	v_sub_f32_e32 v18, v18, v0
	v_sub_f32_e32 v19, v19, v0
	v_sub_f32_e32 v4, v4, v0
	s_nop 0
	v_xor_b32_e32 v48, 0x80000000, v229
	v_mov_b32_e32 v49, v48
	v_mov_b32_e32 v50, v48
	v_mov_b32_e32 v51, v48
	v_mov_b32_e32 v52, v48
	v_mov_b32_e32 v53, v48
	v_mov_b32_e32 v54, v48
	v_mov_b32_e32 v55, v48
	v_mov_b32_e32 v56, v48
	v_mov_b32_e32 v57, v48
	v_mov_b32_e32 v58, v48
	v_mov_b32_e32 v59, v48
	v_mov_b32_e32 v60, v48
	v_mov_b32_e32 v61, v48
	v_mov_b32_e32 v62, v48
	v_mov_b32_e32 v63, v48
	s_waitcnt vmcnt(0) lgkmcnt(0)
	s_barrier
	v_exp_f32_e32 v80, v2
	v_exp_f32_e32 v81, v3
	v_lshl_add_u64 v[2:3], v[212:213], 0, s[22:23]
	s_mov_b32 s22, m0
	s_mov_b32 m0, s74
	s_nop 0
	global_load_lds_dwordx4 v[2:3], off
	s_mov_b32 m0, s22
	s_cselect_b32 s22, 0, 0
	s_add_i32 s16, s22, s16
	v_lshl_add_u64 v[2:3], v[214:215], 0, s[30:31]
	s_add_i32 s16, s16, 0x8000
	s_mov_b32 s22, m0
	s_mov_b32 m0, s16
	s_nop 0
	global_load_lds_dwordx4 v[2:3], off
	s_mov_b32 m0, s22
	ds_read_b128 v[188:191], v228 offset:8192
	ds_read_b128 v[184:187], v228 offset:8704
	ds_read_b128 v[180:183], v228 offset:10240
	ds_read_b128 v[176:179], v228 offset:10752
	ds_read_b128 v[172:175], v228 offset:12288
	ds_read_b128 v[168:171], v228 offset:12800
	ds_read_b128 v[164:167], v228 offset:14336
	ds_read_b128 v[160:163], v228 offset:14848
	v_sub_f32_e32 v20, v20, v0
	v_sub_f32_e32 v5, v5, v0
	v_sub_f32_e32 v21, v21, v0
	v_sub_f32_e32 v6, v6, v0
	v_sub_f32_e32 v22, v22, v0
	v_sub_f32_e32 v7, v7, v0
	v_sub_f32_e32 v23, v23, v0
	v_sub_f32_e32 v8, v8, v0
	v_sub_f32_e32 v24, v24, v0
	v_sub_f32_e32 v9, v9, v0
	v_sub_f32_e32 v25, v25, v0
	v_sub_f32_e32 v10, v10, v0
	v_sub_f32_e32 v26, v26, v0
	v_sub_f32_e32 v11, v11, v0
	v_sub_f32_e32 v27, v27, v0
	v_sub_f32_e32 v12, v12, v0
	v_sub_f32_e32 v28, v28, v0
	v_sub_f32_e32 v13, v13, v0
	v_sub_f32_e32 v29, v29, v0
	v_sub_f32_e32 v14, v14, v0
	v_sub_f32_e32 v30, v30, v0
	v_sub_f32_e32 v15, v15, v0
	v_sub_f32_e32 v31, v31, v0
	v_sub_f32_e32 v16, v16, v0
	v_sub_f32_e32 v32, v32, v0
	v_sub_f32_e32 v17, v17, v0
	v_sub_f32_e32 v0, v33, v0
	v_exp_f32_e32 v82, v4
	v_exp_f32_e32 v83, v5
	v_exp_f32_e32 v84, v6
	v_exp_f32_e32 v85, v7
	v_exp_f32_e32 v86, v8
	v_exp_f32_e32 v87, v9
	v_exp_f32_e32 v88, v10
	v_exp_f32_e32 v89, v11
	v_exp_f32_e32 v90, v12
	v_exp_f32_e32 v91, v13
	v_exp_f32_e32 v92, v14
	v_exp_f32_e32 v93, v15
	v_exp_f32_e32 v94, v16
	v_exp_f32_e32 v95, v17
	v_exp_f32_e32 v64, v18
	v_exp_f32_e32 v65, v19
	v_exp_f32_e32 v66, v20
	v_exp_f32_e32 v67, v21
	v_exp_f32_e32 v68, v22
	v_exp_f32_e32 v69, v23
	v_exp_f32_e32 v70, v24
	v_exp_f32_e32 v71, v25
	v_exp_f32_e32 v72, v26
	v_exp_f32_e32 v73, v27
	v_exp_f32_e32 v74, v28
	v_exp_f32_e32 v75, v29
	v_exp_f32_e32 v76, v30
	v_exp_f32_e32 v77, v31
	v_exp_f32_e32 v78, v32
	v_exp_f32_e32 v79, v0
	s_waitcnt vmcnt(2) lgkmcnt(0)
	s_barrier
	s_andn2_b64 vcc, exec, s[2:3]
	v_cmp_gt_u32_e64 s[2:3], 32, v217
	v_lshl_add_u32 v226, v218, 2, s17
	v_lshl_add_u32 v224, v221, 2, s17
	s_cbranch_vccnz .LBB0_1330
	v_mov_b32_e32 v14, v1
	v_mov_b32_e32 v15, v1
	v_readlane_b32 s16, v255, 9
	v_mov_b32_e32 v0, v1
	v_mov_b32_e32 v2, v1
	v_mov_b32_e32 v3, v1
	v_mov_b32_e32 v4, v1
	v_mov_b32_e32 v5, v1
	v_mov_b32_e32 v6, v1
	v_mov_b32_e32 v7, v1
	v_mov_b32_e32 v8, v1
	v_mov_b32_e32 v9, v1
	v_mov_b32_e32 v10, v1
	v_mov_b32_e32 v11, v1
	v_mov_b32_e32 v12, v1
	v_mov_b32_e32 v13, v1
	v_mov_b64_e32 v[46:47], v[14:15]
	v_mov_b64_e32 v[30:31], v[14:15]
	v_lshl_add_u32 v200, v219, 4, s16
	s_mov_b32 s16, 0
	s_movk_i32 s25, 0x4000
	s_movk_i32 s50, 0x2000
	v_mov_b32_e32 v241, 0
	s_mov_b32 s46, 6
	s_mov_b32 s47, 0x20000
	v_mov_b64_e32 v[44:45], v[12:13]
	v_mov_b64_e32 v[42:43], v[10:11]
	v_mov_b64_e32 v[40:41], v[8:9]
	v_mov_b64_e32 v[38:39], v[6:7]
	v_mov_b64_e32 v[36:37], v[4:5]
	v_mov_b64_e32 v[34:35], v[2:3]
	v_mov_b64_e32 v[32:33], v[0:1]
	v_mov_b64_e32 v[28:29], v[12:13]
	v_mov_b64_e32 v[26:27], v[10:11]
	v_mov_b64_e32 v[24:25], v[8:9]
	v_mov_b64_e32 v[22:23], v[6:7]
	v_mov_b64_e32 v[20:21], v[4:5]
	v_mov_b64_e32 v[18:19], v[2:3]
	v_mov_b64_e32 v[16:17], v[0:1]
	.p2align	6

.LBB0_1331:
	s_xor_b64 s[16:17], s[4:5], -1
	s_add_i32 s2, s50, 1
	s_cmp_ge_u32 s2, s77
	s_cbranch_scc1 .LBB0_1381
	s_lshl_b32 s4, s50, 6
	s_addk_i32 s4, 0x7b
	v_add_u32_e32 v0, s4, v221
	s_lshl_b32 s4, s24, 2
	s_sub_i32 s65, 0, s4
	s_lshl_b32 s4, s50, 8
	s_add_i32 s4, s4, 0
	s_add_i32 s4, s4, 0x14800
	v_cmp_gt_u32_e64 s[2:3], 32, v217
	v_subrev_u32_e32 v0, s71, v0
	s_add_i32 s58, s50, 2
	v_lshl_add_u32 v14, v219, 4, s4
	s_lshl_b32 s79, s50, 15
	.p2align	6

.LBB0_1472:
	v_bfe_u32 v134, v0, 4, 2
	v_and_b32_e32 v135, 15, v0
	v_lshlrev_b32_e32 v2, 4, v134
	v_lshlrev_b32_e32 v0, 2, v0
	s_lshl_b32 s48, s8, 6
	v_lshl_or_b32 v2, v135, 6, v2
	s_lshl_b32 s8, s8, 13
	v_and_b32_e32 v0, 32, v0
	v_bitop3_b32 v4, v2, s8, v0 bitop3:0xde
	s_lshl_b32 s8, s9, 5
	s_and_b32 s49, s8, 0x60
	s_lshl_b32 s8, s49, 7
	v_bitop3_b32 v136, s8, v2, v0 bitop3:0xf6
	v_mov_b32_e32 v0, v131
	s_waitcnt vmcnt(2)
	s_barrier
	s_add_i32 m0, s42, 0x18000
	v_lshl_add_u64 v[2:3], s[6:7], 0, v[0:1]
	v_lshl_add_u64 v[2:3], v[2:3], 0, s[38:39]
	v_mov_b32_e32 v0, v133
	global_load_lds_dwordx4 v[2:3], off
	s_add_i32 m0, s42, 0x1a000
	v_lshl_add_u64 v[2:3], s[6:7], 0, v[0:1]
	v_lshl_add_u64 v[2:3], v[2:3], 0, s[38:39]
	v_mov_b32_e32 v0, v130
	global_load_lds_dwordx4 v[2:3], off
	s_add_i32 s58, s42, 0x8000
	v_lshl_add_u64 v[2:3], s[4:5], 0, v[0:1]
	v_lshl_add_u64 v[2:3], v[2:3], 0, s[38:39]
	s_mov_b32 m0, s58
	v_mov_b32_e32 v0, v132
	global_load_lds_dwordx4 v[2:3], off
	s_add_i32 s59, s42, 0xa000
	v_lshl_add_u64 v[2:3], s[4:5], 0, v[0:1]
	v_lshl_add_u64 v[2:3], v[2:3], 0, s[38:39]
	s_mov_b32 m0, s59
	s_add_u32 s8, s6, 0x40080
	v_mov_b32_e32 v0, v131
	global_load_lds_dwordx4 v[2:3], off
	s_addc_u32 s9, s7, 0
	s_add_i32 m0, s42, 0x1c000
	v_mov_b32_e32 v2, 0
	global_load_lds_dwordx4 v0, s[8:9]
	v_mov_b32_e32 v0, v133
	s_add_i32 m0, s42, 0x1e000
	s_mov_b64 s[14:15], 0
	global_load_lds_dwordx4 v0, s[8:9]
	s_waitcnt vmcnt(6)
	s_mov_b64 s[8:9], -1
	s_mov_b64 s[12:13], 0
	v_add_u32_e32 v137, 0, v4
	v_mov_b32_e32 v3, v2
	v_mov_b32_e32 v4, v2
	v_mov_b32_e32 v5, v2
	v_mov_b32_e32 v6, v2
	v_mov_b32_e32 v7, v2
	v_mov_b32_e32 v8, v2
	v_mov_b32_e32 v9, v2
	v_mov_b32_e32 v10, v2
	v_mov_b32_e32 v11, v2
	v_mov_b32_e32 v12, v2
	v_mov_b32_e32 v13, v2
	v_mov_b32_e32 v18, v2
	v_mov_b32_e32 v19, v2
	v_mov_b32_e32 v20, v2
	v_mov_b32_e32 v21, v2
	v_mov_b32_e32 v26, v2
	v_mov_b32_e32 v27, v2
	v_mov_b32_e32 v28, v2
	v_mov_b32_e32 v29, v2
	v_mov_b32_e32 v34, v2
	v_mov_b32_e32 v35, v2
	v_mov_b32_e32 v36, v2
	v_mov_b32_e32 v37, v2
	v_mov_b32_e32 v42, v2
	v_mov_b32_e32 v43, v2
	v_mov_b32_e32 v44, v2
	v_mov_b32_e32 v45, v2
	v_mov_b32_e32 v50, v2
	v_mov_b32_e32 v51, v2
	v_mov_b32_e32 v52, v2
	v_mov_b32_e32 v53, v2
	v_mov_b32_e32 v14, v2
	v_mov_b32_e32 v15, v2
	v_mov_b32_e32 v16, v2
	v_mov_b32_e32 v17, v2
	v_mov_b32_e32 v22, v2
	v_mov_b32_e32 v23, v2
	v_mov_b32_e32 v24, v2
	v_mov_b32_e32 v25, v2
	v_mov_b32_e32 v30, v2
	v_mov_b32_e32 v31, v2
	v_mov_b32_e32 v32, v2
	v_mov_b32_e32 v33, v2
	v_mov_b32_e32 v38, v2
	v_mov_b32_e32 v39, v2
	v_mov_b32_e32 v40, v2
	v_mov_b32_e32 v41, v2
	v_mov_b32_e32 v46, v2
	v_mov_b32_e32 v47, v2
	v_mov_b32_e32 v48, v2
	v_mov_b32_e32 v49, v2
	v_mov_b32_e32 v54, v2
	v_mov_b32_e32 v55, v2
	v_mov_b32_e32 v56, v2
	v_mov_b32_e32 v57, v2
	v_mov_b32_e32 v58, v2
	v_mov_b32_e32 v59, v2
	v_mov_b32_e32 v60, v2
	v_mov_b32_e32 v61, v2
	v_mov_b32_e32 v66, v2
	v_mov_b32_e32 v67, v2
	v_mov_b32_e32 v68, v2
	v_mov_b32_e32 v69, v2
	v_mov_b32_e32 v62, v2
	v_mov_b32_e32 v63, v2
	v_mov_b32_e32 v64, v2
	v_mov_b32_e32 v65, v2
	v_mov_b32_e32 v70, v2
	v_mov_b32_e32 v71, v2
	v_mov_b32_e32 v72, v2
	v_mov_b32_e32 v73, v2
	v_mov_b32_e32 v74, v2
	v_mov_b32_e32 v75, v2
	v_mov_b32_e32 v76, v2
	v_mov_b32_e32 v77, v2
	v_mov_b32_e32 v82, v2
	v_mov_b32_e32 v83, v2
	v_mov_b32_e32 v84, v2
	v_mov_b32_e32 v85, v2
	v_mov_b32_e32 v90, v2
	v_mov_b32_e32 v91, v2
	v_mov_b32_e32 v92, v2
	v_mov_b32_e32 v93, v2
	v_mov_b32_e32 v98, v2
	v_mov_b32_e32 v99, v2
	v_mov_b32_e32 v100, v2
	v_mov_b32_e32 v101, v2
	v_mov_b32_e32 v106, v2
	v_mov_b32_e32 v107, v2
	v_mov_b32_e32 v108, v2
	v_mov_b32_e32 v109, v2
	v_mov_b32_e32 v114, v2
	v_mov_b32_e32 v115, v2
	v_mov_b32_e32 v116, v2
	v_mov_b32_e32 v117, v2
	v_mov_b32_e32 v78, v2
	v_mov_b32_e32 v79, v2
	v_mov_b32_e32 v80, v2
	v_mov_b32_e32 v81, v2
	v_mov_b32_e32 v86, v2
	v_mov_b32_e32 v87, v2
	v_mov_b32_e32 v88, v2
	v_mov_b32_e32 v89, v2
	v_mov_b32_e32 v94, v2
	v_mov_b32_e32 v95, v2
	v_mov_b32_e32 v96, v2
	v_mov_b32_e32 v97, v2
	v_mov_b32_e32 v102, v2
	v_mov_b32_e32 v103, v2
	v_mov_b32_e32 v104, v2
	v_mov_b32_e32 v105, v2
	v_mov_b32_e32 v110, v2
	v_mov_b32_e32 v111, v2
	v_mov_b32_e32 v112, v2
	v_mov_b32_e32 v113, v2
	v_mov_b32_e32 v118, v2
	v_mov_b32_e32 v119, v2
	v_mov_b32_e32 v120, v2
	v_mov_b32_e32 v121, v2
	v_mov_b32_e32 v122, v2
	v_mov_b32_e32 v123, v2
	v_mov_b32_e32 v124, v2
	v_mov_b32_e32 v125, v2
	v_mov_b32_e32 v126, v2
	v_mov_b32_e32 v127, v2
	v_mov_b32_e32 v128, v2
	v_mov_b32_e32 v129, v2
	s_barrier
	.p2align	6

.LBB0_1480:
	v_bfe_u32 v134, v2, 4, 2
	s_add_u32 s51, s6, 0x800
	v_and_b32_e32 v135, 15, v2
	v_lshlrev_b32_e32 v0, 4, v134
	v_lshlrev_b32_e32 v2, 2, v2
	s_addc_u32 s58, s7, 0
	s_lshl_b32 s48, s8, 6
	v_lshl_or_b32 v0, v135, 6, v0
	s_lshl_b32 s8, s8, 13
	v_and_b32_e32 v2, 32, v2
	v_bitop3_b32 v4, v0, s8, v2 bitop3:0xde
	s_lshl_b32 s8, s9, 5
	s_and_b32 s49, s8, 0x60
	s_lshl_b32 s8, s49, 7
	v_bitop3_b32 v136, s8, v0, v2 bitop3:0xf6
	v_mov_b32_e32 v0, v131
	s_waitcnt vmcnt(2)
	s_barrier
	s_mov_b64 s[8:9], 0x880
	v_lshl_add_u64 v[2:3], s[6:7], 0, v[0:1]
	s_add_i32 m0, s41, 0x18000
	v_lshl_add_u64 v[2:3], v[2:3], 0, s[8:9]
	v_mov_b32_e32 v0, v133
	global_load_lds_dwordx4 v[2:3], off
	s_add_i32 m0, s41, 0x1a000
	v_lshl_add_u64 v[2:3], s[6:7], 0, v[0:1]
	v_lshl_add_u64 v[2:3], v[2:3], 0, s[8:9]
	v_mov_b32_e32 v0, v130
	global_load_lds_dwordx4 v[2:3], off
	s_add_i32 s59, s41, 0x8000
	v_lshl_add_u64 v[2:3], s[4:5], 0, v[0:1]
	v_lshl_add_u64 v[2:3], v[2:3], 0, s[38:39]
	s_mov_b32 m0, s59
	v_mov_b32_e32 v0, v132
	global_load_lds_dwordx4 v[2:3], off
	s_add_i32 s60, s41, 0xa000
	v_lshl_add_u64 v[2:3], s[4:5], 0, v[0:1]
	v_lshl_add_u64 v[2:3], v[2:3], 0, s[38:39]
	s_mov_b32 m0, s60
	s_add_u32 s8, s6, 0x80880
	v_mov_b32_e32 v0, v131
	global_load_lds_dwordx4 v[2:3], off
	s_addc_u32 s9, s7, 0
	s_add_i32 m0, s41, 0x1c000
	v_mov_b32_e32 v2, 0
	global_load_lds_dwordx4 v0, s[8:9]
	v_mov_b32_e32 v0, v133
	s_add_i32 m0, s41, 0x1e000
	s_mov_b64 s[14:15], 0
	global_load_lds_dwordx4 v0, s[8:9]
	s_waitcnt vmcnt(6)
	s_mov_b64 s[8:9], -1
	s_mov_b64 s[12:13], 0
	v_add_u32_e32 v137, 0, v4
	v_mov_b32_e32 v3, v2
	v_mov_b32_e32 v4, v2
	v_mov_b32_e32 v5, v2
	v_mov_b32_e32 v6, v2
	v_mov_b32_e32 v7, v2
	v_mov_b32_e32 v8, v2
	v_mov_b32_e32 v9, v2
	v_mov_b32_e32 v10, v2
	v_mov_b32_e32 v11, v2
	v_mov_b32_e32 v12, v2
	v_mov_b32_e32 v13, v2
	v_mov_b32_e32 v18, v2
	v_mov_b32_e32 v19, v2
	v_mov_b32_e32 v20, v2
	v_mov_b32_e32 v21, v2
	v_mov_b32_e32 v26, v2
	v_mov_b32_e32 v27, v2
	v_mov_b32_e32 v28, v2
	v_mov_b32_e32 v29, v2
	v_mov_b32_e32 v34, v2
	v_mov_b32_e32 v35, v2
	v_mov_b32_e32 v36, v2
	v_mov_b32_e32 v37, v2
	v_mov_b32_e32 v42, v2
	v_mov_b32_e32 v43, v2
	v_mov_b32_e32 v44, v2
	v_mov_b32_e32 v45, v2
	v_mov_b32_e32 v50, v2
	v_mov_b32_e32 v51, v2
	v_mov_b32_e32 v52, v2
	v_mov_b32_e32 v53, v2
	v_mov_b32_e32 v14, v2
	v_mov_b32_e32 v15, v2
	v_mov_b32_e32 v16, v2
	v_mov_b32_e32 v17, v2
	v_mov_b32_e32 v22, v2
	v_mov_b32_e32 v23, v2
	v_mov_b32_e32 v24, v2
	v_mov_b32_e32 v25, v2
	v_mov_b32_e32 v30, v2
	v_mov_b32_e32 v31, v2
	v_mov_b32_e32 v32, v2
	v_mov_b32_e32 v33, v2
	v_mov_b32_e32 v38, v2
	v_mov_b32_e32 v39, v2
	v_mov_b32_e32 v40, v2
	v_mov_b32_e32 v41, v2
	v_mov_b32_e32 v46, v2
	v_mov_b32_e32 v47, v2
	v_mov_b32_e32 v48, v2
	v_mov_b32_e32 v49, v2
	v_mov_b32_e32 v54, v2
	v_mov_b32_e32 v55, v2
	v_mov_b32_e32 v56, v2
	v_mov_b32_e32 v57, v2
	v_mov_b32_e32 v58, v2
	v_mov_b32_e32 v59, v2
	v_mov_b32_e32 v60, v2
	v_mov_b32_e32 v61, v2
	v_mov_b32_e32 v66, v2
	v_mov_b32_e32 v67, v2
	v_mov_b32_e32 v68, v2
	v_mov_b32_e32 v69, v2
	v_mov_b32_e32 v62, v2
	v_mov_b32_e32 v63, v2
	v_mov_b32_e32 v64, v2
	v_mov_b32_e32 v65, v2
	v_mov_b32_e32 v70, v2
	v_mov_b32_e32 v71, v2
	v_mov_b32_e32 v72, v2
	v_mov_b32_e32 v73, v2
	v_mov_b32_e32 v74, v2
	v_mov_b32_e32 v75, v2
	v_mov_b32_e32 v76, v2
	v_mov_b32_e32 v77, v2
	v_mov_b32_e32 v82, v2
	v_mov_b32_e32 v83, v2
	v_mov_b32_e32 v84, v2
	v_mov_b32_e32 v85, v2
	v_mov_b32_e32 v90, v2
	v_mov_b32_e32 v91, v2
	v_mov_b32_e32 v92, v2
	v_mov_b32_e32 v93, v2
	v_mov_b32_e32 v98, v2
	v_mov_b32_e32 v99, v2
	v_mov_b32_e32 v100, v2
	v_mov_b32_e32 v101, v2
	v_mov_b32_e32 v106, v2
	v_mov_b32_e32 v107, v2
	v_mov_b32_e32 v108, v2
	v_mov_b32_e32 v109, v2
	v_mov_b32_e32 v114, v2
	v_mov_b32_e32 v115, v2
	v_mov_b32_e32 v116, v2
	v_mov_b32_e32 v117, v2
	v_mov_b32_e32 v78, v2
	v_mov_b32_e32 v79, v2
	v_mov_b32_e32 v80, v2
	v_mov_b32_e32 v81, v2
	v_mov_b32_e32 v86, v2
	v_mov_b32_e32 v87, v2
	v_mov_b32_e32 v88, v2
	v_mov_b32_e32 v89, v2
	v_mov_b32_e32 v94, v2
	v_mov_b32_e32 v95, v2
	v_mov_b32_e32 v96, v2
	v_mov_b32_e32 v97, v2
	v_mov_b32_e32 v102, v2
	v_mov_b32_e32 v103, v2
	v_mov_b32_e32 v104, v2
	v_mov_b32_e32 v105, v2
	v_mov_b32_e32 v110, v2
	v_mov_b32_e32 v111, v2
	v_mov_b32_e32 v112, v2
	v_mov_b32_e32 v113, v2
	v_mov_b32_e32 v118, v2
	v_mov_b32_e32 v119, v2
	v_mov_b32_e32 v120, v2
	v_mov_b32_e32 v121, v2
	v_mov_b32_e32 v122, v2
	v_mov_b32_e32 v123, v2
	v_mov_b32_e32 v124, v2
	v_mov_b32_e32 v125, v2
	v_mov_b32_e32 v126, v2
	v_mov_b32_e32 v127, v2
	v_mov_b32_e32 v128, v2
	v_mov_b32_e32 v129, v2
	s_barrier
	.p2align	6

.LBB0_1569:
	s_waitcnt vmcnt(0)
	v_add_f32_e32 v6, v6, v7
	v_add_f32_e32 v7, v8, v9
	v_add_f32_e32 v2, v2, v3
	v_add_f32_e32 v3, v4, v5
	s_lshr_b32 s13, s65, 6
	v_add_f32_e32 v6, v6, v7
	v_add_f32_e32 v2, v2, v3
	s_lshl_b32 s10, s13, 19
	v_add_f32_e32 v2, v6, v2
	s_add_u32 s25, s37, s10
	v_fmamk_f32 v2, v2, 0x3b000000, v231
	s_addc_u32 s26, s64, 0
	v_rsq_f32_e32 v138, v2
	s_and_b32 s12, s7, 3
	v_lshlrev_b32_e32 v2, 1, v66
	v_lshrrev_b32_e32 v3, 2, v66
	v_and_b32_e32 v4, 3, v67
	s_mov_b32 s7, 0x1fffe0
	v_and_b32_e32 v2, 24, v2
	v_and_b32_e32 v3, 4, v3
	v_and_or_b32 v4, v66, s7, v4
	v_or3_b32 v2, v4, v3, v2
	v_lshl_add_u32 v167, v2, 11, v68
	v_lshlrev_b32_e32 v2, 1, v69
	v_lshrrev_b32_e32 v3, 2, v69
	v_and_b32_e32 v4, 3, v70
	v_and_b32_e32 v2, 24, v2
	v_and_b32_e32 v3, 4, v3
	v_and_or_b32 v4, v69, s7, v4
	v_or3_b32 v2, v4, v3, v2
	v_bfe_u32 v240, v0, 4, 2
	v_or_b32_e32 v0, s9, v165
	v_lshl_add_u32 v168, v2, 11, v71
	v_lshlrev_b32_e32 v4, 4, v240
	v_lshlrev_b32_e32 v2, 6, v0
	s_movk_i32 s7, 0x3c0
	v_lshlrev_b32_e32 v6, 2, v0
	v_mov_b32_e32 v0, v164
	v_and_or_b32 v5, v2, s7, v4
	s_waitcnt vmcnt(2)
	s_barrier
	s_add_i32 s37, s17, 0x8000
	v_lshl_add_u64 v[2:3], s[2:3], 0, v[0:1]
	v_lshl_add_u64 v[2:3], v[2:3], 0, s[38:39]
	s_mov_b32 m0, s37
	v_mov_b32_e32 v0, v166
	global_load_lds_dwordx4 v[2:3], off
	s_add_i32 s40, s17, 0xa000
	v_lshl_add_u64 v[2:3], s[2:3], 0, v[0:1]
	v_lshl_add_u64 v[2:3], v[2:3], 0, s[38:39]
	s_mov_b32 m0, s40
	v_mov_b32_e32 v72, v58
	global_load_lds_dwordx4 v[2:3], off
	v_mov_b32_e32 v73, v42
	v_mov_b32_e32 v42, v59
	v_mov_b32_e32 v58, v60
	v_mov_b32_e32 v59, v44
	v_mov_b32_e32 v44, v61
	v_pk_add_f32 v[42:43], v[72:73], v[42:43]
	v_pk_add_f32 v[44:45], v[58:59], v[44:45]
	v_add_f32_e32 v34, v34, v35
	v_pk_add_f32 v[42:43], v[42:43], v[44:45]
	v_add_f32_e32 v35, v36, v37
	v_add_f32_e32 v42, v42, v43
	v_fmamk_f32 v42, v42, 0x3b000000, v231
	v_rsq_f32_e32 v116, v42
	v_add_f32_e32 v42, v62, v63
	v_add_f32_e32 v43, v64, v65
	v_add_f32_e32 v42, v42, v43
	v_add_f32_e32 v34, v34, v35
	v_add_f32_e32 v34, v42, v34
	v_fmamk_f32 v34, v34, 0x3b000000, v231
	v_rsq_f32_e32 v118, v34
	v_add_f32_e32 v34, v54, v55
	v_add_f32_e32 v35, v56, v57
	v_add_f32_e32 v26, v26, v27
	v_add_f32_e32 v27, v28, v29
	v_add_f32_e32 v34, v34, v35
	v_add_f32_e32 v26, v26, v27
	v_add_f32_e32 v26, v34, v26
	v_fmamk_f32 v26, v26, 0x3b000000, v231
	v_rsq_f32_e32 v124, v26
	v_add_f32_e32 v26, v50, v51
	v_add_f32_e32 v27, v52, v53
	v_add_f32_e32 v18, v18, v19
	v_add_f32_e32 v19, v20, v21
	v_add_f32_e32 v26, v26, v27
	v_add_f32_e32 v18, v18, v19
	v_add_f32_e32 v18, v26, v18
	v_fmamk_f32 v18, v18, 0x3b000000, v231
	v_rsq_f32_e32 v126, v18
	v_add_f32_e32 v18, v38, v39
	v_add_f32_e32 v19, v40, v41
	v_add_f32_e32 v18, v18, v19
	v_add_f32_e32 v19, v22, v23
	v_add_f32_e32 v20, v24, v25
	v_add_f32_e32 v19, v19, v20
	v_add_f32_e32 v18, v18, v19
	v_fmamk_f32 v18, v18, 0x3b000000, v231
	v_rsq_f32_e32 v132, v18
	v_add_f32_e32 v18, v30, v31
	v_add_f32_e32 v19, v32, v33
	v_add_f32_e32 v10, v10, v11
	v_add_f32_e32 v11, v12, v13
	s_lshl_b32 s7, s8, 13
	v_and_b32_e32 v0, 32, v6
	v_add_f32_e32 v18, v18, v19
	v_add_f32_e32 v19, v46, v47
	v_add_f32_e32 v20, v48, v49
	v_add_f32_e32 v10, v10, v11
	v_add_f32_e32 v11, v14, v15
	v_add_f32_e32 v12, v16, v17
	v_bitop3_b32 v5, v5, s7, v0 bitop3:0xde
	s_lshl_b32 s7, s12, 12
	v_add_f32_e32 v19, v19, v20
	v_add_f32_e32 v11, v11, v12
	s_add_u32 s41, s4, s6
	v_add_f32_e32 v18, v18, v19
	v_add_f32_e32 v10, v10, v11
	v_lshlrev_b32_e32 v2, 2, v165
	s_addc_u32 s42, s5, 0
	v_readlane_b32 s6, v255, 16
	v_fmamk_f32 v18, v18, 0x3b000000, v231
	v_fmamk_f32 v10, v10, 0x3b000000, v231
	v_lshl_or_b32 v0, v165, 6, v4
	v_and_b32_e32 v2, 32, v2
	s_add_u32 s6, s4, s6
	v_rsq_f32_e32 v134, v18
	v_rsq_f32_e32 v136, v10
	v_bitop3_b32 v169, v0, s7, v2 bitop3:0xde
	s_addc_u32 s7, s5, 0
	s_add_u32 s6, s6, s10
	s_waitcnt vmcnt(2)
	s_addc_u32 s7, s7, 0
	v_mov_b32_e32 v2, v1
	v_mov_b32_e32 v3, v1
	s_add_u32 s43, s6, 0x1280100
	v_mov_b32_e32 v0, v1
	v_add_u32_e32 v170, 0, v5
	v_mov_b64_e32 v[6:7], v[2:3]
	v_mov_b64_e32 v[10:11], v[2:3]
	v_mov_b64_e32 v[22:23], v[2:3]
	v_mov_b64_e32 v[26:27], v[2:3]
	v_mov_b64_e32 v[38:39], v[2:3]
	v_mov_b64_e32 v[42:43], v[2:3]
	v_mov_b64_e32 v[54:55], v[2:3]
	v_mov_b64_e32 v[58:59], v[2:3]
	v_mov_b64_e32 v[14:15], v[2:3]
	v_mov_b64_e32 v[18:19], v[2:3]
	v_mov_b64_e32 v[30:31], v[2:3]
	v_mov_b64_e32 v[34:35], v[2:3]
	v_mov_b64_e32 v[46:47], v[2:3]
	v_mov_b64_e32 v[50:51], v[2:3]
	v_mov_b64_e32 v[62:63], v[2:3]
	v_mov_b64_e32 v[66:67], v[2:3]
	v_mov_b64_e32 v[70:71], v[2:3]
	v_mov_b64_e32 v[74:75], v[2:3]
	v_mov_b64_e32 v[86:87], v[2:3]
	v_mov_b64_e32 v[90:91], v[2:3]
	v_mov_b64_e32 v[102:103], v[2:3]
	v_mov_b64_e32 v[106:107], v[2:3]
	v_mov_b64_e32 v[122:123], v[2:3]
	v_mov_b64_e32 v[130:131], v[2:3]
	v_mov_b64_e32 v[78:79], v[2:3]
	v_mov_b64_e32 v[82:83], v[2:3]
	v_mov_b64_e32 v[94:95], v[2:3]
	v_mov_b64_e32 v[98:99], v[2:3]
	v_mov_b64_e32 v[110:111], v[2:3]
	v_mov_b64_e32 v[114:115], v[2:3]
	v_mov_b64_e32 v[158:159], v[2:3]
	v_mov_b64_e32 v[162:163], v[2:3]
	v_mov_b32_e32 v117, v116
	v_mov_b32_e32 v140, v116
	v_mov_b32_e32 v141, v116
	v_mov_b32_e32 v119, v118
	v_mov_b32_e32 v142, v118
	v_mov_b32_e32 v143, v118
	v_mov_b32_e32 v125, v124
	v_mov_b32_e32 v144, v124
	v_mov_b32_e32 v145, v124
	v_mov_b32_e32 v127, v126
	v_mov_b32_e32 v146, v126
	v_mov_b32_e32 v147, v126
	v_mov_b32_e32 v133, v132
	v_mov_b32_e32 v148, v132
	v_mov_b32_e32 v149, v132
	v_mov_b32_e32 v135, v134
	v_mov_b32_e32 v150, v134
	v_mov_b32_e32 v151, v134
	v_mov_b32_e32 v137, v136
	v_mov_b32_e32 v152, v136
	v_mov_b32_e32 v153, v136
	v_mov_b32_e32 v139, v138
	v_mov_b32_e32 v154, v138
	v_mov_b32_e32 v155, v138
	s_addc_u32 s46, s7, 0
	s_mov_b32 s47, -2
	s_mov_b64 s[6:7], 0
	v_mov_b64_e32 v[4:5], v[0:1]
	v_mov_b64_e32 v[8:9], v[0:1]
	v_mov_b64_e32 v[20:21], v[0:1]
	v_mov_b64_e32 v[24:25], v[0:1]
	v_mov_b64_e32 v[36:37], v[0:1]
	v_mov_b64_e32 v[40:41], v[0:1]
	v_mov_b64_e32 v[52:53], v[0:1]
	v_mov_b64_e32 v[56:57], v[0:1]
	v_mov_b64_e32 v[12:13], v[0:1]
	v_mov_b64_e32 v[16:17], v[0:1]
	v_mov_b64_e32 v[28:29], v[0:1]
	v_mov_b64_e32 v[32:33], v[0:1]
	v_mov_b64_e32 v[44:45], v[0:1]
	v_mov_b64_e32 v[48:49], v[0:1]
	v_mov_b64_e32 v[60:61], v[0:1]
	v_mov_b64_e32 v[64:65], v[0:1]
	v_mov_b64_e32 v[68:69], v[0:1]
	v_mov_b64_e32 v[72:73], v[0:1]
	v_mov_b64_e32 v[84:85], v[0:1]
	v_mov_b64_e32 v[88:89], v[0:1]
	v_mov_b64_e32 v[100:101], v[0:1]
	v_mov_b64_e32 v[104:105], v[0:1]
	v_mov_b64_e32 v[120:121], v[0:1]
	v_mov_b64_e32 v[128:129], v[0:1]
	v_mov_b64_e32 v[76:77], v[0:1]
	v_mov_b64_e32 v[80:81], v[0:1]
	v_mov_b64_e32 v[92:93], v[0:1]
	v_mov_b64_e32 v[96:97], v[0:1]
	v_mov_b64_e32 v[108:109], v[0:1]
	v_mov_b64_e32 v[112:113], v[0:1]
	v_mov_b64_e32 v[156:157], v[0:1]
	v_mov_b64_e32 v[160:161], v[0:1]
	s_barrier
	s_branch .LBB0_1571
	.p2align	6

.LBB0_1680:
	s_add_u32 s37, s8, 0x100
	s_addc_u32 s40, s9, 0
	s_and_b32 s16, s2, 3
	v_lshlrev_b32_e32 v8, 1, v2
	v_lshrrev_b32_e32 v9, 2, v2
	v_and_b32_e32 v3, 3, v3
	s_mov_b32 s2, 0x1fffe0
	v_and_b32_e32 v8, 24, v8
	v_and_b32_e32 v9, 4, v9
	v_and_or_b32 v2, v2, s2, v3
	v_or3_b32 v2, v2, v9, v8
	v_lshl_add_u32 v134, v2, 11, v4
	v_lshlrev_b32_e32 v2, 1, v5
	v_lshrrev_b32_e32 v3, 2, v5
	v_and_b32_e32 v4, 3, v6
	v_and_b32_e32 v2, 24, v2
	v_and_b32_e32 v3, 4, v3
	v_and_or_b32 v4, v5, s2, v4
	v_or3_b32 v2, v4, v3, v2
	v_bfe_u32 v131, v0, 4, 2
	v_lshl_add_u32 v135, v2, 11, v7
	v_and_b32_e32 v133, 15, v0
	v_lshlrev_b32_e32 v2, 4, v131
	v_lshlrev_b32_e32 v0, 2, v0
	v_lshl_or_b32 v2, v133, 6, v2
	s_lshl_b32 s2, s3, 13
	v_and_b32_e32 v0, 32, v0
	v_bitop3_b32 v4, v2, s2, v0 bitop3:0xde
	s_lshl_b32 s2, s16, 12
	v_bitop3_b32 v136, v2, s2, v0 bitop3:0xde
	v_mov_b32_e32 v0, v130
	s_waitcnt vmcnt(2)
	s_barrier
	s_add_i32 s42, s23, 0x8000
	v_lshl_add_u64 v[2:3], s[6:7], 0, v[0:1]
	v_lshl_add_u64 v[2:3], v[2:3], 0, s[38:39]
	s_mov_b32 m0, s42
	v_mov_b32_e32 v0, v132
	global_load_lds_dwordx4 v[2:3], off
	s_add_i32 s43, s23, 0xa000
	v_lshl_add_u64 v[2:3], s[6:7], 0, v[0:1]
	v_lshl_add_u64 v[2:3], v[2:3], 0, s[38:39]
	s_mov_b32 m0, s43
	s_lshl_b32 s41, s3, 6
	global_load_lds_dwordx4 v[2:3], off
	s_waitcnt vmcnt(2)
	v_mov_b32_e32 v2, 0
	s_mov_b32 s46, -2
	s_mov_b64 s[2:3], 0
	v_add_u32_e32 v137, 0, v4
	v_mov_b32_e32 v3, v2
	v_mov_b32_e32 v4, v2
	v_mov_b32_e32 v5, v2
	v_mov_b32_e32 v6, v2
	v_mov_b32_e32 v7, v2
	v_mov_b32_e32 v8, v2
	v_mov_b32_e32 v9, v2
	v_mov_b32_e32 v18, v2
	v_mov_b32_e32 v19, v2
	v_mov_b32_e32 v20, v2
	v_mov_b32_e32 v21, v2
	v_mov_b32_e32 v22, v2
	v_mov_b32_e32 v23, v2
	v_mov_b32_e32 v24, v2
	v_mov_b32_e32 v25, v2
	v_mov_b32_e32 v34, v2
	v_mov_b32_e32 v35, v2
	v_mov_b32_e32 v36, v2
	v_mov_b32_e32 v37, v2
	v_mov_b32_e32 v38, v2
	v_mov_b32_e32 v39, v2
	v_mov_b32_e32 v40, v2
	v_mov_b32_e32 v41, v2
	v_mov_b32_e32 v50, v2
	v_mov_b32_e32 v51, v2
	v_mov_b32_e32 v52, v2
	v_mov_b32_e32 v53, v2
	v_mov_b32_e32 v54, v2
	v_mov_b32_e32 v55, v2
	v_mov_b32_e32 v56, v2
	v_mov_b32_e32 v57, v2
	v_mov_b32_e32 v10, v2
	v_mov_b32_e32 v11, v2
	v_mov_b32_e32 v12, v2
	v_mov_b32_e32 v13, v2
	v_mov_b32_e32 v14, v2
	v_mov_b32_e32 v15, v2
	v_mov_b32_e32 v16, v2
	v_mov_b32_e32 v17, v2
	v_mov_b32_e32 v26, v2
	v_mov_b32_e32 v27, v2
	v_mov_b32_e32 v28, v2
	v_mov_b32_e32 v29, v2
	v_mov_b32_e32 v30, v2
	v_mov_b32_e32 v31, v2
	v_mov_b32_e32 v32, v2
	v_mov_b32_e32 v33, v2
	v_mov_b32_e32 v42, v2
	v_mov_b32_e32 v43, v2
	v_mov_b32_e32 v44, v2
	v_mov_b32_e32 v45, v2
	v_mov_b32_e32 v46, v2
	v_mov_b32_e32 v47, v2
	v_mov_b32_e32 v48, v2
	v_mov_b32_e32 v49, v2
	v_mov_b32_e32 v58, v2
	v_mov_b32_e32 v59, v2
	v_mov_b32_e32 v60, v2
	v_mov_b32_e32 v61, v2
	v_mov_b32_e32 v62, v2
	v_mov_b32_e32 v63, v2
	v_mov_b32_e32 v64, v2
	v_mov_b32_e32 v65, v2
	v_mov_b32_e32 v66, v2
	v_mov_b32_e32 v67, v2
	v_mov_b32_e32 v68, v2
	v_mov_b32_e32 v69, v2
	v_mov_b32_e32 v70, v2
	v_mov_b32_e32 v71, v2
	v_mov_b32_e32 v72, v2
	v_mov_b32_e32 v73, v2
	v_mov_b32_e32 v82, v2
	v_mov_b32_e32 v83, v2
	v_mov_b32_e32 v84, v2
	v_mov_b32_e32 v85, v2
	v_mov_b32_e32 v86, v2
	v_mov_b32_e32 v87, v2
	v_mov_b32_e32 v88, v2
	v_mov_b32_e32 v89, v2
	v_mov_b32_e32 v98, v2
	v_mov_b32_e32 v99, v2
	v_mov_b32_e32 v100, v2
	v_mov_b32_e32 v101, v2
	v_mov_b32_e32 v102, v2
	v_mov_b32_e32 v103, v2
	v_mov_b32_e32 v104, v2
	v_mov_b32_e32 v105, v2
	v_mov_b32_e32 v114, v2
	v_mov_b32_e32 v115, v2
	v_mov_b32_e32 v116, v2
	v_mov_b32_e32 v117, v2
	v_mov_b32_e32 v118, v2
	v_mov_b32_e32 v119, v2
	v_mov_b32_e32 v120, v2
	v_mov_b32_e32 v121, v2
	v_mov_b32_e32 v74, v2
	v_mov_b32_e32 v75, v2
	v_mov_b32_e32 v76, v2
	v_mov_b32_e32 v77, v2
	v_mov_b32_e32 v78, v2
	v_mov_b32_e32 v79, v2
	v_mov_b32_e32 v80, v2
	v_mov_b32_e32 v81, v2
	v_mov_b32_e32 v90, v2
	v_mov_b32_e32 v91, v2
	v_mov_b32_e32 v92, v2
	v_mov_b32_e32 v93, v2
	v_mov_b32_e32 v94, v2
	v_mov_b32_e32 v95, v2
	v_mov_b32_e32 v96, v2
	v_mov_b32_e32 v97, v2
	v_mov_b32_e32 v106, v2
	v_mov_b32_e32 v107, v2
	v_mov_b32_e32 v108, v2
	v_mov_b32_e32 v109, v2
	v_mov_b32_e32 v110, v2
	v_mov_b32_e32 v111, v2
	v_mov_b32_e32 v112, v2
	v_mov_b32_e32 v113, v2
	v_mov_b32_e32 v122, v2
	v_mov_b32_e32 v123, v2
	v_mov_b32_e32 v124, v2
	v_mov_b32_e32 v125, v2
	v_mov_b32_e32 v126, v2
	v_mov_b32_e32 v127, v2
	v_mov_b32_e32 v128, v2
	v_mov_b32_e32 v129, v2
	s_barrier
	.p2align	6

.LBB0_1806:
	s_add_u32 s50, s12, 0x100
	s_addc_u32 s51, s13, 0
	s_and_b32 s61, s14, 3
	v_lshlrev_b32_e32 v8, 1, v2
	v_lshrrev_b32_e32 v9, 2, v2
	v_and_b32_e32 v3, 3, v3
	s_mov_b32 s14, 0x1fffe0
	v_and_b32_e32 v8, 24, v8
	v_and_b32_e32 v9, 4, v9
	v_and_or_b32 v2, v2, s14, v3
	v_or3_b32 v2, v2, v9, v8
	v_lshl_add_u32 v124, v2, 11, v4
	v_lshlrev_b32_e32 v2, 1, v5
	v_lshrrev_b32_e32 v3, 2, v5
	v_and_b32_e32 v4, 3, v6
	v_and_b32_e32 v2, 24, v2
	v_and_b32_e32 v3, 4, v3
	v_and_or_b32 v4, v5, s14, v4
	v_or3_b32 v2, v4, v3, v2
	v_bfe_u32 v158, v0, 4, 2
	v_lshl_add_u32 v125, v2, 11, v7
	v_and_b32_e32 v159, 15, v0
	v_lshlrev_b32_e32 v2, 4, v158
	v_lshlrev_b32_e32 v0, 2, v0
	v_lshl_or_b32 v2, v159, 6, v2
	s_lshl_b32 s14, s24, 13
	v_and_b32_e32 v0, 32, v0
	v_bitop3_b32 v4, v2, s14, v0 bitop3:0xde
	s_lshl_b32 s14, s61, 12
	v_bitop3_b32 v126, v2, s14, v0 bitop3:0xde
	v_mov_b32_e32 v0, v122
	s_waitcnt vmcnt(2)
	s_barrier
	s_add_i32 s64, s43, 0x8000
	v_lshl_add_u64 v[2:3], s[4:5], 0, v[0:1]
	v_lshl_add_u64 v[2:3], v[2:3], 0, s[38:39]
	s_mov_b32 m0, s64
	v_mov_b32_e32 v0, v123
	global_load_lds_dwordx4 v[2:3], off
	s_add_i32 s65, s43, 0xa000
	v_lshl_add_u64 v[2:3], s[4:5], 0, v[0:1]
	v_lshl_add_u64 v[2:3], v[2:3], 0, s[38:39]
	s_mov_b32 m0, s65
	s_lshl_b32 s49, s24, 6
	global_load_lds_dwordx4 v[2:3], off
	s_waitcnt vmcnt(2)
	v_mov_b32_e32 v2, 0
	s_mov_b32 s66, -2
	s_mov_b64 s[14:15], 0
	v_add_u32_e32 v127, 0, v4
	v_mov_b32_e32 v3, v2
	v_mov_b32_e32 v4, v2
	v_mov_b32_e32 v5, v2
	v_mov_b32_e32 v6, v2
	v_mov_b32_e32 v7, v2
	v_mov_b32_e32 v8, v2
	v_mov_b32_e32 v9, v2
	v_mov_b32_e32 v18, v2
	v_mov_b32_e32 v19, v2
	v_mov_b32_e32 v20, v2
	v_mov_b32_e32 v21, v2
	v_mov_b32_e32 v22, v2
	v_mov_b32_e32 v23, v2
	v_mov_b32_e32 v24, v2
	v_mov_b32_e32 v25, v2
	v_mov_b32_e32 v34, v2
	v_mov_b32_e32 v35, v2
	v_mov_b32_e32 v36, v2
	v_mov_b32_e32 v37, v2
	v_mov_b32_e32 v38, v2
	v_mov_b32_e32 v39, v2
	v_mov_b32_e32 v40, v2
	v_mov_b32_e32 v41, v2
	v_mov_b32_e32 v50, v2
	v_mov_b32_e32 v51, v2
	v_mov_b32_e32 v52, v2
	v_mov_b32_e32 v53, v2
	v_mov_b32_e32 v54, v2
	v_mov_b32_e32 v55, v2
	v_mov_b32_e32 v56, v2
	v_mov_b32_e32 v57, v2
	v_mov_b32_e32 v10, v2
	v_mov_b32_e32 v11, v2
	v_mov_b32_e32 v12, v2
	v_mov_b32_e32 v13, v2
	v_mov_b32_e32 v14, v2
	v_mov_b32_e32 v15, v2
	v_mov_b32_e32 v16, v2
	v_mov_b32_e32 v17, v2
	v_mov_b32_e32 v26, v2
	v_mov_b32_e32 v27, v2
	v_mov_b32_e32 v28, v2
	v_mov_b32_e32 v29, v2
	v_mov_b32_e32 v30, v2
	v_mov_b32_e32 v31, v2
	v_mov_b32_e32 v32, v2
	v_mov_b32_e32 v33, v2
	v_mov_b32_e32 v42, v2
	v_mov_b32_e32 v43, v2
	v_mov_b32_e32 v44, v2
	v_mov_b32_e32 v45, v2
	v_mov_b32_e32 v46, v2
	v_mov_b32_e32 v47, v2
	v_mov_b32_e32 v48, v2
	v_mov_b32_e32 v49, v2
	v_mov_b32_e32 v58, v2
	v_mov_b32_e32 v59, v2
	v_mov_b32_e32 v60, v2
	v_mov_b32_e32 v61, v2
	v_mov_b32_e32 v62, v2
	v_mov_b32_e32 v63, v2
	v_mov_b32_e32 v64, v2
	v_mov_b32_e32 v65, v2
	v_mov_b32_e32 v66, v2
	v_mov_b32_e32 v67, v2
	v_mov_b32_e32 v68, v2
	v_mov_b32_e32 v69, v2
	v_mov_b32_e32 v70, v2
	v_mov_b32_e32 v71, v2
	v_mov_b32_e32 v72, v2
	v_mov_b32_e32 v73, v2
	v_mov_b32_e32 v82, v2
	v_mov_b32_e32 v83, v2
	v_mov_b32_e32 v84, v2
	v_mov_b32_e32 v85, v2
	v_mov_b32_e32 v86, v2
	v_mov_b32_e32 v87, v2
	v_mov_b32_e32 v88, v2
	v_mov_b32_e32 v89, v2
	v_mov_b32_e32 v98, v2
	v_mov_b32_e32 v99, v2
	v_mov_b32_e32 v100, v2
	v_mov_b32_e32 v101, v2
	v_mov_b32_e32 v102, v2
	v_mov_b32_e32 v103, v2
	v_mov_b32_e32 v104, v2
	v_mov_b32_e32 v105, v2
	v_mov_b32_e32 v114, v2
	v_mov_b32_e32 v115, v2
	v_mov_b32_e32 v116, v2
	v_mov_b32_e32 v117, v2
	v_mov_b32_e32 v118, v2
	v_mov_b32_e32 v119, v2
	v_mov_b32_e32 v120, v2
	v_mov_b32_e32 v121, v2
	v_mov_b32_e32 v74, v2
	v_mov_b32_e32 v75, v2
	v_mov_b32_e32 v76, v2
	v_mov_b32_e32 v77, v2
	v_mov_b32_e32 v78, v2
	v_mov_b32_e32 v79, v2
	v_mov_b32_e32 v80, v2
	v_mov_b32_e32 v81, v2
	v_mov_b32_e32 v90, v2
	v_mov_b32_e32 v91, v2
	v_mov_b32_e32 v92, v2
	v_mov_b32_e32 v93, v2
	v_mov_b32_e32 v94, v2
	v_mov_b32_e32 v95, v2
	v_mov_b32_e32 v96, v2
	v_mov_b32_e32 v97, v2
	v_mov_b32_e32 v106, v2
	v_mov_b32_e32 v107, v2
	v_mov_b32_e32 v108, v2
	v_mov_b32_e32 v109, v2
	v_mov_b32_e32 v110, v2
	v_mov_b32_e32 v111, v2
	v_mov_b32_e32 v112, v2
	v_mov_b32_e32 v113, v2
	v_mov_b32_e32 v134, v2
	v_mov_b32_e32 v135, v2
	v_mov_b32_e32 v136, v2
	v_mov_b32_e32 v137, v2
	v_mov_b32_e32 v138, v2
	v_mov_b32_e32 v139, v2
	v_mov_b32_e32 v140, v2
	v_mov_b32_e32 v141, v2
	s_barrier
	.p2align	6

.LBB0_1885:
	s_lshr_b32 s12, s37, 6
	s_lshl_b32 s43, s12, 19
	s_add_u32 s13, s76, s43
	s_addc_u32 s25, s77, 0
	s_lshl_b32 s7, s7, 20
	s_add_u32 s26, s13, s7
	s_addc_u32 s40, s25, 0
	s_and_b32 s13, s4, 3
	v_lshlrev_b32_e32 v8, 1, v2
	v_lshrrev_b32_e32 v9, 2, v2
	v_and_b32_e32 v3, 3, v3
	s_mov_b32 s4, 0x1fffe0
	v_and_b32_e32 v8, 24, v8
	v_and_b32_e32 v9, 4, v9
	v_and_or_b32 v2, v2, s4, v3
	v_or3_b32 v2, v2, v9, v8
	v_lshl_add_u32 v125, v2, 11, v4
	v_lshlrev_b32_e32 v2, 1, v5
	v_lshrrev_b32_e32 v3, 2, v5
	v_and_b32_e32 v4, 3, v6
	v_and_b32_e32 v2, 24, v2
	v_and_b32_e32 v3, 4, v3
	v_and_or_b32 v4, v5, s4, v4
	v_or3_b32 v2, v4, v3, v2
	v_bfe_u32 v240, v0, 4, 2
	v_lshl_add_u32 v126, v2, 11, v7
	v_and_b32_e32 v124, 15, v0
	v_lshlrev_b32_e32 v2, 4, v240
	v_lshlrev_b32_e32 v0, 2, v0
	v_lshl_or_b32 v2, v124, 6, v2
	s_lshl_b32 s4, s6, 13
	v_and_b32_e32 v0, 32, v0
	v_bitop3_b32 v4, v2, s4, v0 bitop3:0xde
	s_lshl_b32 s4, s13, 12
	v_bitop3_b32 v127, v2, s4, v0 bitop3:0xde
	v_mov_b32_e32 v0, v122
	s_waitcnt vmcnt(2)
	s_barrier
	s_add_i32 s41, s17, 0x8000
	v_lshl_add_u64 v[2:3], s[2:3], 0, v[0:1]
	v_lshl_add_u64 v[2:3], v[2:3], 0, s[38:39]
	s_mov_b32 m0, s41
	v_mov_b32_e32 v0, v123
	global_load_lds_dwordx4 v[2:3], off
	s_add_i32 s42, s17, 0xa000
	v_lshl_add_u64 v[2:3], s[2:3], 0, v[0:1]
	v_lshl_add_u64 v[2:3], v[2:3], 0, s[38:39]
	s_mov_b32 m0, s42
	s_and_b32 s4, s37, 7
	global_load_lds_dwordx4 v[2:3], off
	s_mul_i32 s4, s4, 0xc00000
	s_mul_i32 s5, s5, 0x180000
	s_lshl_b32 s25, s6, 6
	s_add_i32 s4, s4, s5
	s_add_u32 s4, s8, s4
	s_addc_u32 s5, s9, 0
	s_add_u32 s4, s4, 0x9840080
	s_addc_u32 s5, s5, 0
	v_readlane_b32 s46, v255, 20
	v_readlane_b32 s47, v255, 21
	s_add_u32 s6, s10, s46
	s_addc_u32 s10, s11, s47
	s_add_u32 s7, s7, s43
	s_addc_u32 s11, 0, 0
	s_add_u32 s6, s6, s7
	s_waitcnt vmcnt(2)
	s_addc_u32 s7, s10, s11
	s_add_u32 s37, s6, 0x200100
	v_mov_b32_e32 v2, 0
	s_addc_u32 s43, s7, 0
	s_mov_b32 s46, -2
	v_add_u32_e32 v128, 0, v4
	v_mov_b32_e32 v3, v2
	v_mov_b32_e32 v4, v2
	v_mov_b32_e32 v5, v2
	v_mov_b32_e32 v6, v2
	v_mov_b32_e32 v7, v2
	v_mov_b32_e32 v8, v2
	v_mov_b32_e32 v9, v2
	v_mov_b32_e32 v18, v2
	v_mov_b32_e32 v19, v2
	v_mov_b32_e32 v20, v2
	v_mov_b32_e32 v21, v2
	v_mov_b32_e32 v22, v2
	v_mov_b32_e32 v23, v2
	v_mov_b32_e32 v24, v2
	v_mov_b32_e32 v25, v2
	v_mov_b32_e32 v34, v2
	v_mov_b32_e32 v35, v2
	v_mov_b32_e32 v36, v2
	v_mov_b32_e32 v37, v2
	v_mov_b32_e32 v38, v2
	v_mov_b32_e32 v39, v2
	v_mov_b32_e32 v40, v2
	v_mov_b32_e32 v41, v2
	v_mov_b32_e32 v50, v2
	v_mov_b32_e32 v51, v2
	v_mov_b32_e32 v52, v2
	v_mov_b32_e32 v53, v2
	v_mov_b32_e32 v54, v2
	v_mov_b32_e32 v55, v2
	v_mov_b32_e32 v56, v2
	v_mov_b32_e32 v57, v2
	v_mov_b32_e32 v10, v2
	v_mov_b32_e32 v11, v2
	v_mov_b32_e32 v12, v2
	v_mov_b32_e32 v13, v2
	v_mov_b32_e32 v14, v2
	v_mov_b32_e32 v15, v2
	v_mov_b32_e32 v16, v2
	v_mov_b32_e32 v17, v2
	v_mov_b32_e32 v26, v2
	v_mov_b32_e32 v27, v2
	v_mov_b32_e32 v28, v2
	v_mov_b32_e32 v29, v2
	v_mov_b32_e32 v30, v2
	v_mov_b32_e32 v31, v2
	v_mov_b32_e32 v32, v2
	v_mov_b32_e32 v33, v2
	v_mov_b32_e32 v42, v2
	v_mov_b32_e32 v43, v2
	v_mov_b32_e32 v44, v2
	v_mov_b32_e32 v45, v2
	v_mov_b32_e32 v46, v2
	v_mov_b32_e32 v47, v2
	v_mov_b32_e32 v48, v2
	v_mov_b32_e32 v49, v2
	v_mov_b32_e32 v58, v2
	v_mov_b32_e32 v59, v2
	v_mov_b32_e32 v60, v2
	v_mov_b32_e32 v61, v2
	v_mov_b32_e32 v62, v2
	v_mov_b32_e32 v63, v2
	v_mov_b32_e32 v64, v2
	v_mov_b32_e32 v65, v2
	v_mov_b32_e32 v66, v2
	v_mov_b32_e32 v67, v2
	v_mov_b32_e32 v68, v2
	v_mov_b32_e32 v69, v2
	v_mov_b32_e32 v70, v2
	v_mov_b32_e32 v71, v2
	v_mov_b32_e32 v72, v2
	v_mov_b32_e32 v73, v2
	v_mov_b32_e32 v82, v2
	v_mov_b32_e32 v83, v2
	v_mov_b32_e32 v84, v2
	v_mov_b32_e32 v85, v2
	v_mov_b32_e32 v86, v2
	v_mov_b32_e32 v87, v2
	v_mov_b32_e32 v88, v2
	v_mov_b32_e32 v89, v2
	v_mov_b32_e32 v98, v2
	v_mov_b32_e32 v99, v2
	v_mov_b32_e32 v100, v2
	v_mov_b32_e32 v101, v2
	v_mov_b32_e32 v102, v2
	v_mov_b32_e32 v103, v2
	v_mov_b32_e32 v104, v2
	v_mov_b32_e32 v105, v2
	v_mov_b32_e32 v114, v2
	v_mov_b32_e32 v115, v2
	v_mov_b32_e32 v116, v2
	v_mov_b32_e32 v117, v2
	v_mov_b32_e32 v118, v2
	v_mov_b32_e32 v119, v2
	v_mov_b32_e32 v120, v2
	v_mov_b32_e32 v121, v2
	v_mov_b32_e32 v74, v2
	v_mov_b32_e32 v75, v2
	v_mov_b32_e32 v76, v2
	v_mov_b32_e32 v77, v2
	v_mov_b32_e32 v78, v2
	v_mov_b32_e32 v79, v2
	v_mov_b32_e32 v80, v2
	v_mov_b32_e32 v81, v2
	v_mov_b32_e32 v90, v2
	v_mov_b32_e32 v91, v2
	v_mov_b32_e32 v92, v2
	v_mov_b32_e32 v93, v2
	v_mov_b32_e32 v94, v2
	v_mov_b32_e32 v95, v2
	v_mov_b32_e32 v96, v2
	v_mov_b32_e32 v97, v2
	v_mov_b32_e32 v106, v2
	v_mov_b32_e32 v107, v2
	v_mov_b32_e32 v108, v2
	v_mov_b32_e32 v109, v2
	v_mov_b32_e32 v110, v2
	v_mov_b32_e32 v111, v2
	v_mov_b32_e32 v112, v2
	v_mov_b32_e32 v113, v2
	v_mov_b32_e32 v150, v2
	v_mov_b32_e32 v151, v2
	v_mov_b32_e32 v152, v2
	v_mov_b32_e32 v153, v2
	v_mov_b32_e32 v154, v2
	v_mov_b32_e32 v155, v2
	v_mov_b32_e32 v156, v2
	v_mov_b32_e32 v157, v2
	s_barrier
	.p2align	6
